# nt cache-policy hint on the once-read f32 weight / x loads of the weight-conversion phase (on top of register-ring scan)
# speedup vs baseline: 1.0085x; 1.0038x over previous
; DI void phase_weights(KArgs args, LAS unsigned char* lds, const Ctx& c) {
;     ...
;     for (int it = gw; it < NITEMS; it += NGW) {
;         int r = it;
;         const float* src; long sld; int sc0, nv = 32, kv; bf16_t* dst; long dld; int dr0, k0;
;         if (r < 16 * 112) { const int kb = r / 112, nb = r % 112, n0 = 32 * nb; src = args->in[2] + (size_t)l * D * DIN; sld = DIN; kv = D;
;             sc0 = n0; nv = 3480 - n0; if (nv < 0) { nv = 0; sc0 = 0; } if (nv > 32) nv = 32;
;             dst = WSP(bf16_t, WS_WIN); dld = D; dr0 = n0; k0 = 64 * kb; }
;         else if (r < I_IN) { const int q = r - 16 * 112, kb = q / 96, nb = q % 96;
;             if (q < 16 * 96) tr_item8(args->in[2] + (size_t)l * D * DIN, DIN, 3480 + 32 * nb, D, WSP(unsigned char, WS_WG8), D, 32 * nb, 64 * kb, 32.0f, scr, lane);
;             else { const int q2 = q - 16 * 96, kb2 = q2 / 64, nb2 = q2 % 64;
;                 tr_item8(args->in[2] + (size_t)l * D * DIN, DIN, 32 * nb2, D, WSP(unsigned char, WS_WG8), D, 3072 + 32 * nb2, 64 * kb2, 32.0f, scr, lane); }
;             continue; }
;         else if ((r -= I_IN) < I_NA) { const int kb = r / 32, nb = r % 32; src = args->in[8] + (size_t)l * 256 * D; sld = D; sc0 = 32 * nb; kv = 256; dst = WSP(bf16_t, WS_WBR); dld = 768; dr0 = 32 * nb; k0 = 64 * kb; }
;         else if ((r -= I_NA) < I_DIL) { const int kb = r / 32, nb = r % 32; src = args->in[9] + (size_t)l * 128 * D; sld = D; sc0 = 32 * nb; kv = 128; dst = WSP(bf16_t, WS_WBR) + 256; dld = 768; dr0 = 32 * nb; k0 = 64 * kb; }
;         else if ((r -= I_DIL) < I_GDN) { const int kb = r / 32, nb = r % 32; src = args->in[10] + (size_t)l * 384 * D; sld = D; sc0 = 32 * nb; kv = 384; dst = WSP(bf16_t, WS_WBR) + 384; dld = 768; dr0 = 32 * nb; k0 = 64 * kb; }
;         else if ((r -= I_GDN) < I_OUT) { const int kb = r / 32, nb = r % 32; tr_item8(args->in[11] + (size_t)l * D * D, D, 32 * nb, D, WSP(unsigned char, WS_WOUT), D, 32 * nb, 64 * kb, 32.0f, scr, lane); continue; }
;         else if ((r -= I_OUT) < 16 * I_GU1) { const int e = r / I_GU1, q = r % I_GU1, kb = q / 128, nb = q % 128, n0 = 32 * nb, j = n0 >> 8, rr = n0 & 255;
;             tr_item8((rr < 128 ? args->in[16] : args->in[15]) + ((size_t)l * NE + e) * D * DE, DE, 128 * j + (rr & 127), D, WSP(unsigned char, WS_WGU) + (size_t)e * 4096 * D, D, n0, 64 * kb, 32.0f, scr, lane); continue; }
.LBB0_18:
	s_mov_b64 s[30:31], -1
	s_mov_b64 s[40:41], 0
	s_cmpk_gt_i32 s58, 0x6ff
	s_mov_b64 s[44:45], -1
	s_cbranch_scc0 .LBB0_167
	s_cmpk_gt_u32 s58, 0x10ff
	s_cbranch_scc0 .LBB0_96
	s_cmpk_gt_u32 s58, 0x117f
	s_cbranch_scc0 .LBB0_97
	s_cmpk_gt_u32 s58, 0x11bf
	s_cbranch_scc0 .LBB0_237
	s_cmpk_gt_u32 s58, 0x127f
	s_mov_b64 s[34:35], -1
	s_cbranch_scc0 .LBB0_94
	s_cmpk_gt_u32 s58, 0x147f
	s_cbranch_scc0 .LBB0_29
	s_cmpk_gt_u32 s58, 0x947f
	s_cbranch_scc0 .LBB0_26
	s_load_dwordx2 s[34:35], s[6:7], 0x88
	s_add_i32 s36, s58, 0xffff6b80
	s_lshr_b32 s92, s36, 10
	v_mov_b32_e32 v15, v3
	s_waitcnt lgkmcnt(0)
	s_add_u32 s36, s34, s14
	s_addc_u32 s37, s35, s15
	s_lshl_b64 s[34:35], s[92:93], 23
	s_add_u32 s38, s36, s34
	s_addc_u32 s39, s37, s35
	s_and_b32 s34, s51, 0x3e0
	s_lshl_b64 s[36:37], s[92:93], 21
	s_add_u32 s36, s11, s36
	s_addc_u32 s35, s13, s37
	s_add_i32 s37, s54, 0xfffed700
	s_and_b32 s37, s37, 0x7c0
	s_lshl_b32 s40, s34, 2
	s_add_u32 s38, s38, s40
	v_or_b32_e32 v14, s37, v16
	s_addc_u32 s39, s39, 0
	v_lshl_add_u64 v[12:13], s[38:39], 0, v[2:3]
	v_lshlrev_b32_e32 v14, 12, v14
	v_lshl_add_u64 v[12:13], v[12:13], 0, v[14:15]
	v_add_co_u32_e32 v14, vcc, s85, v12
	s_mov_b32 s38, 0x10000
	s_nop 0
	v_addc_co_u32_e32 v15, vcc, 0, v13, vcc
	v_add_co_u32_e32 v30, vcc, s88, v12
	s_add_u32 s36, s36, s37
	s_nop 0
	v_addc_co_u32_e32 v31, vcc, 0, v13, vcc
	v_add_co_u32_e32 v32, vcc, s89, v12
	s_addc_u32 s37, s35, 0
	s_nop 0
	v_addc_co_u32_e32 v33, vcc, 0, v13, vcc
	v_add_co_u32_e32 v34, vcc, s94, v12
	s_nop 1
	v_addc_co_u32_e32 v35, vcc, 0, v13, vcc
	v_add_co_u32_e32 v36, vcc, s66, v12
	s_nop 1
	v_addc_co_u32_e32 v37, vcc, 0, v13, vcc
	v_add_co_u32_e32 v38, vcc, s95, v12
	s_nop 1
	v_addc_co_u32_e32 v39, vcc, 0, v13, vcc
	v_add_co_u32_e32 v40, vcc, s67, v12
	s_nop 1
	v_addc_co_u32_e32 v41, vcc, 0, v13, vcc
	global_load_dword v44, v[12:13], off nt
	global_load_dword v45, v[14:15], off nt
	global_load_dword v46, v[30:31], off nt
	global_load_dword v47, v[32:33], off nt
	global_load_dword v48, v[34:35], off nt
	global_load_dword v49, v[36:37], off nt
	global_load_dword v50, v[38:39], off nt
	global_load_dword v51, v[40:41], off nt
	v_add_co_u32_e32 v14, vcc, s38, v12
	s_mov_b32 s38, 0x12000
	s_nop 0
	v_addc_co_u32_e32 v15, vcc, 0, v13, vcc
	v_add_co_u32_e32 v30, vcc, s38, v12
	s_mov_b32 s38, 0x14000
	s_nop 0
	v_addc_co_u32_e32 v31, vcc, 0, v13, vcc
	v_add_co_u32_e32 v32, vcc, s38, v12
	s_mov_b32 s38, 0x16000
	s_nop 0
	v_addc_co_u32_e32 v33, vcc, 0, v13, vcc
	v_add_co_u32_e32 v34, vcc, s38, v12
	s_mov_b32 s38, 0x18000
	s_nop 0
	v_addc_co_u32_e32 v35, vcc, 0, v13, vcc
	v_add_co_u32_e32 v36, vcc, s38, v12
	s_mov_b32 s38, 0x1a000
	s_nop 0
	v_addc_co_u32_e32 v37, vcc, 0, v13, vcc
	v_add_co_u32_e32 v38, vcc, s38, v12
	s_mov_b32 s38, 0x1c000
	s_nop 0
	v_addc_co_u32_e32 v39, vcc, 0, v13, vcc
	v_add_co_u32_e32 v40, vcc, s38, v12
	s_mov_b32 s38, 0x1e000
	s_nop 0
	v_addc_co_u32_e32 v41, vcc, 0, v13, vcc
	v_add_co_u32_e32 v42, vcc, s38, v12
	s_mov_b32 s38, 0x20000
	s_nop 0
	v_addc_co_u32_e32 v43, vcc, 0, v13, vcc
	global_load_dword v52, v[14:15], off nt
	global_load_dword v53, v[30:31], off nt
	global_load_dword v54, v[32:33], off nt
	global_load_dword v55, v[34:35], off nt
	global_load_dword v56, v[36:37], off nt
	global_load_dword v57, v[38:39], off nt
	global_load_dword v58, v[40:41], off nt
	global_load_dword v59, v[42:43], off nt
	v_add_co_u32_e32 v14, vcc, s38, v12
	s_mov_b32 s38, 0x22000
	s_nop 0
	v_addc_co_u32_e32 v15, vcc, 0, v13, vcc
	v_add_co_u32_e32 v30, vcc, s38, v12
	s_mov_b32 s38, 0x24000
	s_nop 0
	v_addc_co_u32_e32 v31, vcc, 0, v13, vcc
	v_add_co_u32_e32 v32, vcc, s38, v12
	s_mov_b32 s38, 0x26000
	s_nop 0
	v_addc_co_u32_e32 v33, vcc, 0, v13, vcc
	v_add_co_u32_e32 v34, vcc, s38, v12
	s_mov_b32 s38, 0x28000
	s_nop 0
	v_addc_co_u32_e32 v35, vcc, 0, v13, vcc
	v_add_co_u32_e32 v36, vcc, s38, v12
	s_mov_b32 s38, 0x2a000
	s_nop 0
	v_addc_co_u32_e32 v37, vcc, 0, v13, vcc
	v_add_co_u32_e32 v38, vcc, s38, v12
	s_mov_b32 s38, 0x2c000
	s_nop 0
	v_addc_co_u32_e32 v39, vcc, 0, v13, vcc
	v_add_co_u32_e32 v40, vcc, s38, v12
	s_mov_b32 s38, 0x2e000
	s_nop 0
	v_addc_co_u32_e32 v41, vcc, 0, v13, vcc
	v_add_co_u32_e32 v42, vcc, s38, v12
	s_mov_b32 s38, 0x30000
	s_nop 0
	v_addc_co_u32_e32 v43, vcc, 0, v13, vcc
	global_load_dword v60, v[14:15], off nt
	global_load_dword v61, v[30:31], off nt
	global_load_dword v62, v[32:33], off nt
	global_load_dword v63, v[34:35], off nt
	global_load_dword v64, v[36:37], off nt
	global_load_dword v65, v[38:39], off nt
	global_load_dword v66, v[40:41], off nt
	s_nop 0
	global_load_dword v42, v[42:43], off nt
	v_add_co_u32_e32 v14, vcc, s38, v12
	s_mov_b32 s38, 0x32000
	s_nop 0
	v_addc_co_u32_e32 v15, vcc, 0, v13, vcc
	v_add_co_u32_e32 v30, vcc, s38, v12
	s_mov_b32 s38, 0x34000
	s_nop 0
	v_addc_co_u32_e32 v31, vcc, 0, v13, vcc
	v_add_co_u32_e32 v32, vcc, s38, v12
	s_mov_b32 s38, 0x36000
	s_nop 0
	v_addc_co_u32_e32 v33, vcc, 0, v13, vcc
	v_add_co_u32_e32 v34, vcc, s38, v12
	s_mov_b32 s38, 0x3a000
	s_nop 0
	v_addc_co_u32_e32 v35, vcc, 0, v13, vcc
	v_add_co_u32_e32 v36, vcc, s68, v12
	s_nop 1
	v_addc_co_u32_e32 v37, vcc, 0, v13, vcc
	v_add_co_u32_e32 v38, vcc, s38, v12
	s_mov_b32 s38, 0x3c000
	s_nop 0
	v_addc_co_u32_e32 v39, vcc, 0, v13, vcc
	v_add_co_u32_e32 v40, vcc, s38, v12
	s_mov_b32 s38, 0x3e000
	s_nop 0
	v_addc_co_u32_e32 v41, vcc, 0, v13, vcc
	v_add_co_u32_e32 v12, vcc, s38, v12
	s_nop 1
	v_addc_co_u32_e32 v13, vcc, 0, v13, vcc
	global_load_dword v14, v[14:15], off nt
	s_nop 0
	global_load_dword v15, v[30:31], off nt
	s_nop 0
	global_load_dword v30, v[32:33], off nt
	global_load_dword v31, v[34:35], off nt
	s_nop 0
	global_load_dword v32, v[36:37], off nt
	global_load_dword v33, v[38:39], off nt
	global_load_dword v34, v[40:41], off nt
	s_nop 0
	global_load_dword v12, v[12:13], off nt
	s_waitcnt vmcnt(0)
; #define LAS __attribute__((address_space(3)))
; DI void tr_item8(const float* src, long src_ld, int src_col0, int kvalid, unsigned char* dst, long dst_ld, int dst_row0, int k0, float scale, LAS float* scr, int lane) {
;     ...
; #pragma unroll
;     for (int i = 0; i < 32; ++i) { const int kk = 2 * i + (lane >> 5), cc = lane & 31; scr[kk * 33 + cc] = tv[i]; }
;     asm volatile("s_waitcnt lgkmcnt(0)" ::: "memory");
;     const int c8 = lane & 7;
; #pragma unroll
;     for (int j = 0; j < 4; ++j) { const int n = (lane >> 3) + 8 * j; const LAS float* s = scr + (8 * c8) * 33 + n;
;         u32x2 o; o.x = pk4_fp8(s[0 * 33] * scale, s[1 * 33] * scale, s[2 * 33] * scale, s[3 * 33] * scale); o.y = pk4_fp8(s[4 * 33] * scale, s[5 * 33] * scale, s[6 * 33] * scale, s[7 * 33] * scale);
;         *(u32x2*)(dst + (size_t)(dst_row0 + n) * dst_ld + k0 + 8 * c8) = o; }
;     asm volatile("s_waitcnt lgkmcnt(0)" ::: "memory");
	ds_write2_b32 v17, v44, v45 offset1:66
	s_waitcnt vmcnt(28)
	ds_write2_b32 v17, v46, v47 offset0:132 offset1:198
	s_waitcnt vmcnt(26)
	ds_write2_b32 v23, v48, v49 offset0:8 offset1:74
	s_waitcnt vmcnt(24)
	ds_write2_b32 v23, v50, v51 offset0:140 offset1:206
	s_waitcnt vmcnt(22)
	ds_write2_b32 v24, v52, v53 offset0:16 offset1:82
	s_waitcnt vmcnt(20)
	ds_write2_b32 v24, v54, v55 offset0:148 offset1:214
	s_waitcnt vmcnt(18)
	ds_write2_b32 v25, v56, v57 offset0:24 offset1:90
	s_waitcnt vmcnt(16)
	ds_write2_b32 v25, v58, v59 offset0:156 offset1:222
	s_waitcnt vmcnt(14)
	ds_write2_b32 v26, v60, v61 offset0:32 offset1:98
	s_waitcnt vmcnt(12)
	ds_write2_b32 v26, v62, v63 offset0:164 offset1:230
	s_waitcnt vmcnt(10)
	ds_write2_b32 v27, v64, v65 offset0:40 offset1:106
	s_waitcnt vmcnt(8)
	ds_write2_b32 v27, v66, v42 offset0:172 offset1:238
	s_waitcnt vmcnt(6)
	ds_write2_b32 v28, v14, v15 offset0:48 offset1:114
	s_waitcnt vmcnt(4)
	ds_write2_b32 v28, v30, v31 offset0:180 offset1:246
	s_waitcnt vmcnt(2)
	ds_write2_b32 v29, v32, v33 offset0:56 offset1:122
	s_waitcnt vmcnt(0)
	ds_write2_b32 v29, v34, v12 offset0:188 offset1:254
	s_waitcnt lgkmcnt(0)
	ds_read2_b32 v[12:13], v19 offset1:8
	ds_read2_b32 v[14:15], v19 offset0:33 offset1:41
	ds_read2_b32 v[30:31], v19 offset0:66 offset1:74
	ds_read2_b32 v[34:35], v19 offset0:99 offset1:107
	ds_read2_b32 v[36:37], v19 offset0:132 offset1:140
	ds_read2_b32 v[38:39], v19 offset0:165 offset1:173
	v_mov_b32_e32 v40, v3
	s_waitcnt lgkmcnt(5)
	v_mul_f32_e32 v12, 0x42000000, v12
	s_waitcnt lgkmcnt(4)
	v_mul_f32_e32 v14, 0x42000000, v14
	ds_read2_b32 v[42:43], v19 offset0:198 offset1:206
	ds_read2_b32 v[44:45], v19 offset0:231 offset1:239
	v_cvt_pk_fp8_f32 v40, v12, v14
	s_waitcnt lgkmcnt(3)
	v_mul_f32_e32 v12, 0x42000000, v36
	s_waitcnt lgkmcnt(2)
	v_mul_f32_e32 v14, 0x42000000, v38
	v_mov_b32_e32 v41, v3
	v_cvt_pk_fp8_f32 v41, v12, v14
	s_waitcnt lgkmcnt(1)
	v_mul_f32_e32 v12, 0x42000000, v42
	s_waitcnt lgkmcnt(0)
	v_mul_f32_e32 v14, 0x42000000, v44
	v_mul_f32_e32 v13, 0x42000000, v13
	v_cvt_pk_fp8_f32 v41, v12, v14 op_sel:[0,0,1]
	v_or_b32_e32 v12, s34, v18
	v_lshlrev_b32_e32 v46, 11, v12
	v_mul_f32_e32 v14, 0x42000000, v15
	v_mov_b32_e32 v12, v3
	v_mul_f32_e32 v15, 0x42000000, v31
	v_cvt_pk_fp8_f32 v12, v13, v14
	v_mul_f32_e32 v14, 0x42000000, v37
	v_mul_f32_e32 v31, 0x42000000, v39
	v_mov_b32_e32 v13, v3
	v_cvt_pk_fp8_f32 v13, v14, v31
	v_mul_f32_e32 v30, 0x42000000, v30
	v_mul_f32_e32 v34, 0x42000000, v34
	v_cvt_pk_fp8_f32 v40, v30, v34 op_sel:[0,0,1]
	v_mul_f32_e32 v30, 0x42000000, v35
	v_cvt_pk_fp8_f32 v12, v15, v30 op_sel:[0,0,1]
	v_mul_f32_e32 v14, 0x42000000, v43
	v_mul_f32_e32 v15, 0x42000000, v45
	v_cvt_pk_fp8_f32 v13, v14, v15 op_sel:[0,0,1]
	v_lshl_add_u64 v[32:33], s[36:37], 0, v[6:7]
	v_mov_b32_e32 v47, v3
	v_or_b32_e32 v14, s34, v20
	v_lshl_add_u64 v[46:47], v[32:33], 0, v[46:47]
	v_lshlrev_b32_e32 v14, 11, v14
	v_mov_b32_e32 v15, v3
	global_store_dwordx2 v[46:47], v[40:41], off
	v_lshl_add_u64 v[14:15], v[32:33], 0, v[14:15]
	ds_read2_b32 v[30:31], v19 offset0:16 offset1:24
	ds_read2_b32 v[34:35], v19 offset0:49 offset1:57
	ds_read2_b32 v[36:37], v19 offset0:82 offset1:90
	global_store_dwordx2 v[14:15], v[12:13], off
	ds_read2_b32 v[12:13], v19 offset0:115 offset1:123
	ds_read2_b32 v[14:15], v19 offset0:148 offset1:156
	ds_read2_b32 v[38:39], v19 offset0:181 offset1:189
	s_waitcnt lgkmcnt(5)
	v_mul_f32_e32 v30, 0x42000000, v30
	s_waitcnt lgkmcnt(4)
	v_mul_f32_e32 v34, 0x42000000, v34
	v_mov_b32_e32 v40, v3
	ds_read2_b32 v[42:43], v19 offset0:214 offset1:222
	ds_read2_b32 v[44:45], v19 offset0:247 offset1:255
	v_cvt_pk_fp8_f32 v40, v30, v34
	s_waitcnt lgkmcnt(3)
	v_mul_f32_e32 v14, 0x42000000, v14
	s_waitcnt lgkmcnt(2)
	v_mul_f32_e32 v30, 0x42000000, v38
	v_mov_b32_e32 v41, v3
	v_cvt_pk_fp8_f32 v41, v14, v30
	v_mul_f32_e32 v36, 0x42000000, v36
	v_mul_f32_e32 v12, 0x42000000, v12
	v_cvt_pk_fp8_f32 v40, v36, v12 op_sel:[0,0,1]
	s_waitcnt lgkmcnt(1)
	v_mul_f32_e32 v12, 0x42000000, v42
	s_waitcnt lgkmcnt(0)
	v_mul_f32_e32 v14, 0x42000000, v44
	v_cvt_pk_fp8_f32 v41, v12, v14 op_sel:[0,0,1]
	v_or_b32_e32 v12, s34, v21
	v_lshlrev_b32_e32 v46, 11, v12
	v_mul_f32_e32 v14, 0x42000000, v31
	v_mul_f32_e32 v30, 0x42000000, v35
	v_mov_b32_e32 v12, v3
	v_mul_f32_e32 v34, 0x42000000, v13
	v_cvt_pk_fp8_f32 v12, v14, v30
	v_mul_f32_e32 v14, 0x42000000, v15
	v_mul_f32_e32 v15, 0x42000000, v39
	v_mov_b32_e32 v13, v3
	v_cvt_pk_fp8_f32 v13, v14, v15
	v_mul_f32_e32 v31, 0x42000000, v37
	v_mul_f32_e32 v14, 0x42000000, v43
	v_mul_f32_e32 v15, 0x42000000, v45
	v_cvt_pk_fp8_f32 v12, v31, v34 op_sel:[0,0,1]
	v_cvt_pk_fp8_f32 v13, v14, v15 op_sel:[0,0,1]
	v_or_b32_e32 v14, s34, v22
	v_mov_b32_e32 v47, v3
	v_lshlrev_b32_e32 v14, 11, v14
	v_mov_b32_e32 v15, v3
	v_lshl_add_u64 v[46:47], v[32:33], 0, v[46:47]
	v_lshl_add_u64 v[14:15], v[32:33], 0, v[14:15]
	global_store_dwordx2 v[46:47], v[40:41], off
	global_store_dwordx2 v[14:15], v[12:13], off
	s_waitcnt lgkmcnt(0)
	s_mov_b64 s[34:35], 0
; #define LAS __attribute__((address_space(3)))
; DI void tr_item8(const float* src, long src_ld, int src_col0, int kvalid, unsigned char* dst, long dst_ld, int dst_row0, int k0, float scale, LAS float* scr, int lane) {
;     float tv[32];
; #pragma unroll
;     for (int i = 0; i < 32; ++i) { const int kk = 2 * i + (lane >> 5), cc = lane & 31; tv[i] = 0.f; if ((k0 + kk) < kvalid) tv[i] = src[(size_t)(k0 + kk) * src_ld + src_col0 + cc]; }
; DI void phase_weights(KArgs args, LAS unsigned char* lds, const Ctx& c) {
;     ...
;         else if ((r -= I_OUT) < 16 * I_GU1) { const int e = r / I_GU1, q = r % I_GU1, kb = q / 128, nb = q % 128, n0 = 32 * nb, j = n0 >> 8, rr = n0 & 255;
;             tr_item8((rr < 128 ? args->in[16] : args->in[15]) + ((size_t)l * NE + e) * D * DE, DE, 128 * j + (rr & 127), D, WSP(unsigned char, WS_WGU) + (size_t)e * 4096 * D, D, n0, 64 * kb, 32.0f, scr, lane); continue; }
.LBB0_26:
	s_andn2_b64 vcc, exec, s[34:35]
	s_cbranch_vccnz .LBB0_28
	s_add_i32 s38, s58, 0xffffeb80
	s_lshr_b32 s92, s38, 11
	s_and_b32 s34, s51, 0xfe0
	s_bitcmp0_b32 s58, 2
	s_movk_i32 s35, 0x80
	s_cselect_b32 s35, s35, 0x78
	s_add_u32 s36, s6, s35
	s_addc_u32 s37, s7, 0
	s_load_dwordx2 s[36:37], s[36:37], 0x0
	v_mov_b32_e32 v15, v3
	s_waitcnt lgkmcnt(0)
	s_add_u32 s35, s36, s14
	s_addc_u32 s39, s37, s15
	s_lshl_b64 s[36:37], s[92:93], 23
	s_add_u32 s40, s35, s36
	s_addc_u32 s39, s39, s37
	s_and_b32 s35, s56, 0x780
	s_and_b32 s36, s51, 0x60
	s_or_b32 s41, s35, s36
	s_lshl_b64 s[36:37], s[92:93], 22
	s_add_u32 s36, s49, s36
	s_addc_u32 s35, s50, s37
	s_lshr_b32 s37, s38, 1
	s_and_b32 s37, s37, 0x3c0
	s_lshl_b32 s38, s41, 2
	s_add_u32 s38, s40, s38
	v_or_b32_e32 v14, s37, v16
	s_addc_u32 s39, s39, 0
	v_lshl_add_u64 v[12:13], s[38:39], 0, v[2:3]
	v_lshlrev_b32_e32 v14, 13, v14
	v_lshl_add_u64 v[12:13], v[12:13], 0, v[14:15]
	v_add_co_u32_e32 v14, vcc, s88, v12
	s_mov_b32 s38, 0x10000
	s_nop 0
	v_addc_co_u32_e32 v15, vcc, 0, v13, vcc
	v_add_co_u32_e32 v30, vcc, s94, v12
	s_add_u32 s36, s36, s37
	s_nop 0
	v_addc_co_u32_e32 v31, vcc, 0, v13, vcc
	v_add_co_u32_e32 v32, vcc, s95, v12
	s_addc_u32 s37, s35, 0
	s_nop 0
	v_addc_co_u32_e32 v33, vcc, 0, v13, vcc
	v_add_co_u32_e32 v34, vcc, s38, v12
	s_mov_b32 s38, 0x14000
	s_nop 0
	v_addc_co_u32_e32 v35, vcc, 0, v13, vcc
	v_add_co_u32_e32 v36, vcc, s38, v12
	s_mov_b32 s38, 0x18000
	s_nop 0
	v_addc_co_u32_e32 v37, vcc, 0, v13, vcc
	v_add_co_u32_e32 v38, vcc, s38, v12
	s_mov_b32 s38, 0x1c000
	s_nop 0
	v_addc_co_u32_e32 v39, vcc, 0, v13, vcc
	v_add_co_u32_e32 v40, vcc, s38, v12
	s_mov_b32 s38, 0x20000
	s_nop 0
	v_addc_co_u32_e32 v41, vcc, 0, v13, vcc
	global_load_dword v44, v[12:13], off nt
	global_load_dword v45, v[14:15], off nt
	global_load_dword v46, v[30:31], off nt
	global_load_dword v47, v[32:33], off nt
	global_load_dword v48, v[34:35], off nt
	global_load_dword v49, v[36:37], off nt
	global_load_dword v50, v[38:39], off nt
	global_load_dword v51, v[40:41], off nt
	v_add_co_u32_e32 v14, vcc, s38, v12
	s_mov_b32 s38, 0x24000
	s_nop 0
	v_addc_co_u32_e32 v15, vcc, 0, v13, vcc
	v_add_co_u32_e32 v30, vcc, s38, v12
	s_mov_b32 s38, 0x28000
	s_nop 0
	v_addc_co_u32_e32 v31, vcc, 0, v13, vcc
	v_add_co_u32_e32 v32, vcc, s38, v12
	s_mov_b32 s38, 0x2c000
	s_nop 0
	v_addc_co_u32_e32 v33, vcc, 0, v13, vcc
	v_add_co_u32_e32 v34, vcc, s38, v12
	s_mov_b32 s38, 0x30000
	s_nop 0
	v_addc_co_u32_e32 v35, vcc, 0, v13, vcc
	v_add_co_u32_e32 v36, vcc, s38, v12
	s_mov_b32 s38, 0x34000
	s_nop 0
	v_addc_co_u32_e32 v37, vcc, 0, v13, vcc
	v_add_co_u32_e32 v38, vcc, s38, v12
	s_mov_b32 s38, 0x3c000
	s_nop 0
	v_addc_co_u32_e32 v39, vcc, 0, v13, vcc
	v_add_co_u32_e32 v40, vcc, s68, v12
	s_nop 1
	v_addc_co_u32_e32 v41, vcc, 0, v13, vcc
	v_add_co_u32_e32 v42, vcc, s38, v12
	s_mov_b32 s38, 0x40000
	s_nop 0
	v_addc_co_u32_e32 v43, vcc, 0, v13, vcc
	global_load_dword v52, v[14:15], off nt
	global_load_dword v53, v[30:31], off nt
	global_load_dword v54, v[32:33], off nt
	global_load_dword v55, v[34:35], off nt
	global_load_dword v56, v[36:37], off nt
	global_load_dword v57, v[38:39], off nt
	global_load_dword v58, v[40:41], off nt
	global_load_dword v59, v[42:43], off nt
	v_add_co_u32_e32 v14, vcc, s38, v12
	s_mov_b32 s38, 0x44000
	s_nop 0
	v_addc_co_u32_e32 v15, vcc, 0, v13, vcc
	v_add_co_u32_e32 v30, vcc, s38, v12
	s_mov_b32 s38, 0x48000
	s_nop 0
	v_addc_co_u32_e32 v31, vcc, 0, v13, vcc
	v_add_co_u32_e32 v32, vcc, s38, v12
	s_mov_b32 s38, 0x4c000
	s_nop 0
	v_addc_co_u32_e32 v33, vcc, 0, v13, vcc
	v_add_co_u32_e32 v34, vcc, s38, v12
	s_mov_b32 s38, 0x50000
	s_nop 0
	v_addc_co_u32_e32 v35, vcc, 0, v13, vcc
	v_add_co_u32_e32 v36, vcc, s38, v12
	s_mov_b32 s38, 0x54000
	s_nop 0
	v_addc_co_u32_e32 v37, vcc, 0, v13, vcc
	v_add_co_u32_e32 v38, vcc, s38, v12
	s_mov_b32 s38, 0x58000
	s_nop 0
	v_addc_co_u32_e32 v39, vcc, 0, v13, vcc
	v_add_co_u32_e32 v40, vcc, s38, v12
	s_mov_b32 s38, 0x5c000
	s_nop 0
	v_addc_co_u32_e32 v41, vcc, 0, v13, vcc
	v_add_co_u32_e32 v42, vcc, s38, v12
	s_mov_b32 s38, 0x60000
	s_nop 0
	v_addc_co_u32_e32 v43, vcc, 0, v13, vcc
	global_load_dword v60, v[14:15], off nt
	global_load_dword v61, v[30:31], off nt
	global_load_dword v62, v[32:33], off nt
	global_load_dword v63, v[34:35], off nt
	global_load_dword v64, v[36:37], off nt
	global_load_dword v65, v[38:39], off nt
	global_load_dword v66, v[40:41], off nt
	s_nop 0
	global_load_dword v42, v[42:43], off nt
	v_add_co_u32_e32 v14, vcc, s38, v12
	s_mov_b32 s38, 0x64000
	s_nop 0
	v_addc_co_u32_e32 v15, vcc, 0, v13, vcc
	v_add_co_u32_e32 v30, vcc, s38, v12
	s_mov_b32 s38, 0x68000
	s_nop 0
	v_addc_co_u32_e32 v31, vcc, 0, v13, vcc
	v_add_co_u32_e32 v32, vcc, s38, v12
	s_mov_b32 s38, 0x6c000
	s_nop 0
	v_addc_co_u32_e32 v33, vcc, 0, v13, vcc
	v_add_co_u32_e32 v34, vcc, s38, v12
	s_mov_b32 s38, 0x70000
	s_nop 0
	v_addc_co_u32_e32 v35, vcc, 0, v13, vcc
	v_add_co_u32_e32 v36, vcc, s38, v12
	s_mov_b32 s38, 0x74000
	s_nop 0
	v_addc_co_u32_e32 v37, vcc, 0, v13, vcc
	v_add_co_u32_e32 v38, vcc, s38, v12
	s_mov_b32 s38, 0x78000
	s_nop 0
	v_addc_co_u32_e32 v39, vcc, 0, v13, vcc
	v_add_co_u32_e32 v40, vcc, s38, v12
	s_mov_b32 s38, 0x7c000
	s_nop 0
	v_addc_co_u32_e32 v41, vcc, 0, v13, vcc
	v_add_co_u32_e32 v12, vcc, s38, v12
	s_nop 1
	v_addc_co_u32_e32 v13, vcc, 0, v13, vcc
	global_load_dword v14, v[14:15], off nt
	s_nop 0
	global_load_dword v15, v[30:31], off nt
	s_nop 0
	global_load_dword v30, v[32:33], off nt
	global_load_dword v31, v[34:35], off nt
	s_nop 0
	global_load_dword v32, v[36:37], off nt
	global_load_dword v33, v[38:39], off nt
	global_load_dword v34, v[40:41], off nt
	s_nop 0
	global_load_dword v12, v[12:13], off nt
	s_waitcnt vmcnt(0)
; #define LAS __attribute__((address_space(3)))
; DI void tr_item8(const float* src, long src_ld, int src_col0, int kvalid, unsigned char* dst, long dst_ld, int dst_row0, int k0, float scale, LAS float* scr, int lane) {
;     ...
; #pragma unroll
;     for (int i = 0; i < 32; ++i) { const int kk = 2 * i + (lane >> 5), cc = lane & 31; scr[kk * 33 + cc] = tv[i]; }
;     asm volatile("s_waitcnt lgkmcnt(0)" ::: "memory");
;     const int c8 = lane & 7;
; #pragma unroll
;     for (int j = 0; j < 4; ++j) { const int n = (lane >> 3) + 8 * j; const LAS float* s = scr + (8 * c8) * 33 + n;
;         u32x2 o; o.x = pk4_fp8(s[0 * 33] * scale, s[1 * 33] * scale, s[2 * 33] * scale, s[3 * 33] * scale); o.y = pk4_fp8(s[4 * 33] * scale, s[5 * 33] * scale, s[6 * 33] * scale, s[7 * 33] * scale);
;         *(u32x2*)(dst + (size_t)(dst_row0 + n) * dst_ld + k0 + 8 * c8) = o; }
;     asm volatile("s_waitcnt lgkmcnt(0)" ::: "memory");
	ds_write2_b32 v17, v44, v45 offset1:66
	s_waitcnt vmcnt(28)
	ds_write2_b32 v17, v46, v47 offset0:132 offset1:198
	s_waitcnt vmcnt(26)
	ds_write2_b32 v23, v48, v49 offset0:8 offset1:74
	s_waitcnt vmcnt(24)
	ds_write2_b32 v23, v50, v51 offset0:140 offset1:206
	s_waitcnt vmcnt(22)
	ds_write2_b32 v24, v52, v53 offset0:16 offset1:82
	s_waitcnt vmcnt(20)
	ds_write2_b32 v24, v54, v55 offset0:148 offset1:214
	s_waitcnt vmcnt(18)
	ds_write2_b32 v25, v56, v57 offset0:24 offset1:90
	s_waitcnt vmcnt(16)
	ds_write2_b32 v25, v58, v59 offset0:156 offset1:222
	s_waitcnt vmcnt(14)
	ds_write2_b32 v26, v60, v61 offset0:32 offset1:98
	s_waitcnt vmcnt(12)
	ds_write2_b32 v26, v62, v63 offset0:164 offset1:230
	s_waitcnt vmcnt(10)
	ds_write2_b32 v27, v64, v65 offset0:40 offset1:106
	s_waitcnt vmcnt(8)
	ds_write2_b32 v27, v66, v42 offset0:172 offset1:238
	s_waitcnt vmcnt(6)
	ds_write2_b32 v28, v14, v15 offset0:48 offset1:114
	s_waitcnt vmcnt(4)
	ds_write2_b32 v28, v30, v31 offset0:180 offset1:246
	s_waitcnt vmcnt(2)
	ds_write2_b32 v29, v32, v33 offset0:56 offset1:122
	s_waitcnt vmcnt(0)
	ds_write2_b32 v29, v34, v12 offset0:188 offset1:254
	s_waitcnt lgkmcnt(0)
	ds_read2_b32 v[12:13], v19 offset1:8
	ds_read2_b32 v[14:15], v19 offset0:33 offset1:41
	ds_read2_b32 v[30:31], v19 offset0:66 offset1:74
	ds_read2_b32 v[34:35], v19 offset0:99 offset1:107
	ds_read2_b32 v[36:37], v19 offset0:132 offset1:140
	ds_read2_b32 v[38:39], v19 offset0:165 offset1:173
	v_mov_b32_e32 v40, v3
	s_waitcnt lgkmcnt(5)
	v_mul_f32_e32 v12, 0x42000000, v12
	s_waitcnt lgkmcnt(4)
	v_mul_f32_e32 v14, 0x42000000, v14
	ds_read2_b32 v[42:43], v19 offset0:198 offset1:206
	ds_read2_b32 v[44:45], v19 offset0:231 offset1:239
	v_cvt_pk_fp8_f32 v40, v12, v14
	s_waitcnt lgkmcnt(3)
	v_mul_f32_e32 v12, 0x42000000, v36
	s_waitcnt lgkmcnt(2)
	v_mul_f32_e32 v14, 0x42000000, v38
	v_mov_b32_e32 v41, v3
	v_cvt_pk_fp8_f32 v41, v12, v14
	s_waitcnt lgkmcnt(1)
	v_mul_f32_e32 v12, 0x42000000, v42
	s_waitcnt lgkmcnt(0)
	v_mul_f32_e32 v14, 0x42000000, v44
	v_mul_f32_e32 v13, 0x42000000, v13
	v_cvt_pk_fp8_f32 v41, v12, v14 op_sel:[0,0,1]
	v_or_b32_e32 v12, s34, v18
	v_lshlrev_b32_e32 v46, 10, v12
	v_mul_f32_e32 v14, 0x42000000, v15
	v_mov_b32_e32 v12, v3
	v_mul_f32_e32 v15, 0x42000000, v31
	v_cvt_pk_fp8_f32 v12, v13, v14
	v_mul_f32_e32 v14, 0x42000000, v37
	v_mul_f32_e32 v31, 0x42000000, v39
	v_mov_b32_e32 v13, v3
	v_cvt_pk_fp8_f32 v13, v14, v31
	v_mul_f32_e32 v30, 0x42000000, v30
	v_mul_f32_e32 v34, 0x42000000, v34
	v_cvt_pk_fp8_f32 v40, v30, v34 op_sel:[0,0,1]
	v_mul_f32_e32 v30, 0x42000000, v35
	v_cvt_pk_fp8_f32 v12, v15, v30 op_sel:[0,0,1]
	v_mul_f32_e32 v14, 0x42000000, v43
	v_mul_f32_e32 v15, 0x42000000, v45
	v_cvt_pk_fp8_f32 v13, v14, v15 op_sel:[0,0,1]
	v_lshl_add_u64 v[32:33], s[36:37], 0, v[6:7]
	v_mov_b32_e32 v47, v3
	v_or_b32_e32 v14, s34, v20
	v_lshl_add_u64 v[46:47], v[32:33], 0, v[46:47]
	v_lshlrev_b32_e32 v14, 10, v14
	v_mov_b32_e32 v15, v3
	global_store_dwordx2 v[46:47], v[40:41], off
	v_lshl_add_u64 v[14:15], v[32:33], 0, v[14:15]
	ds_read2_b32 v[30:31], v19 offset0:16 offset1:24
	ds_read2_b32 v[34:35], v19 offset0:49 offset1:57
	ds_read2_b32 v[36:37], v19 offset0:82 offset1:90
	global_store_dwordx2 v[14:15], v[12:13], off
	ds_read2_b32 v[12:13], v19 offset0:115 offset1:123
	ds_read2_b32 v[14:15], v19 offset0:148 offset1:156
	ds_read2_b32 v[38:39], v19 offset0:181 offset1:189
	s_waitcnt lgkmcnt(5)
	v_mul_f32_e32 v30, 0x42000000, v30
	s_waitcnt lgkmcnt(4)
	v_mul_f32_e32 v34, 0x42000000, v34
	v_mov_b32_e32 v40, v3
	ds_read2_b32 v[42:43], v19 offset0:214 offset1:222
	ds_read2_b32 v[44:45], v19 offset0:247 offset1:255
	v_cvt_pk_fp8_f32 v40, v30, v34
	s_waitcnt lgkmcnt(3)
	v_mul_f32_e32 v14, 0x42000000, v14
	s_waitcnt lgkmcnt(2)
	v_mul_f32_e32 v30, 0x42000000, v38
	v_mov_b32_e32 v41, v3
	v_cvt_pk_fp8_f32 v41, v14, v30
	v_mul_f32_e32 v36, 0x42000000, v36
	v_mul_f32_e32 v12, 0x42000000, v12
	v_cvt_pk_fp8_f32 v40, v36, v12 op_sel:[0,0,1]
	s_waitcnt lgkmcnt(1)
	v_mul_f32_e32 v12, 0x42000000, v42
	s_waitcnt lgkmcnt(0)
	v_mul_f32_e32 v14, 0x42000000, v44
	v_cvt_pk_fp8_f32 v41, v12, v14 op_sel:[0,0,1]
	v_or_b32_e32 v12, s34, v21
	v_lshlrev_b32_e32 v46, 10, v12
	v_mul_f32_e32 v14, 0x42000000, v31
	v_mul_f32_e32 v30, 0x42000000, v35
	v_mov_b32_e32 v12, v3
	v_mul_f32_e32 v34, 0x42000000, v13
	v_cvt_pk_fp8_f32 v12, v14, v30
	v_mul_f32_e32 v14, 0x42000000, v15
	v_mul_f32_e32 v15, 0x42000000, v39
	v_mov_b32_e32 v13, v3
	v_cvt_pk_fp8_f32 v13, v14, v15
	v_mul_f32_e32 v31, 0x42000000, v37
	v_mul_f32_e32 v14, 0x42000000, v43
	v_mul_f32_e32 v15, 0x42000000, v45
	v_cvt_pk_fp8_f32 v12, v31, v34 op_sel:[0,0,1]
	v_cvt_pk_fp8_f32 v13, v14, v15 op_sel:[0,0,1]
	v_or_b32_e32 v14, s34, v22
	v_mov_b32_e32 v47, v3
	v_lshlrev_b32_e32 v14, 10, v14
	v_mov_b32_e32 v15, v3
	v_lshl_add_u64 v[46:47], v[32:33], 0, v[46:47]
	v_lshl_add_u64 v[14:15], v[32:33], 0, v[14:15]
	global_store_dwordx2 v[46:47], v[40:41], off
	global_store_dwordx2 v[14:15], v[12:13], off
	s_waitcnt lgkmcnt(0)

; #define LAS __attribute__((address_space(3)))
; DI void tr_item8(const float* src, long src_ld, int src_col0, int kvalid, unsigned char* dst, long dst_ld, int dst_row0, int k0, float scale, LAS float* scr, int lane) {
;     float tv[32];
; #pragma unroll
;     for (int i = 0; i < 32; ++i) { const int kk = 2 * i + (lane >> 5), cc = lane & 31; tv[i] = 0.f; if ((k0 + kk) < kvalid) tv[i] = src[(size_t)(k0 + kk) * src_ld + src_col0 + cc]; }
; DI void phase_weights(KArgs args, LAS unsigned char* lds, const Ctx& c) {
;     ...
;         else if ((r -= I_GDN) < I_OUT) { const int kb = r / 32, nb = r % 32; tr_item8(args->in[11] + (size_t)l * D * D, D, 32 * nb, D, WSP(unsigned char, WS_WOUT), D, 32 * nb, 64 * kb, 32.0f, scr, lane); continue; }
.LBB0_29:
	s_andn2_b64 vcc, exec, s[34:35]
	s_cbranch_vccnz .LBB0_93
	s_load_dwordx2 s[34:35], s[6:7], 0x58
	v_mov_b32_e32 v13, v3
	s_waitcnt lgkmcnt(0)
	s_add_u32 s34, s34, s16
	s_addc_u32 s35, s35, s17
	s_and_b32 s36, s51, 0x3e0
	s_and_b32 s37, s54, 0x3fc0
	s_add_i32 s92, s37, 0xffffdb00
	s_lshl_b32 s37, s36, 2
	s_add_u32 s34, s34, s37
	v_or_b32_e32 v12, s92, v16
	s_addc_u32 s35, s35, 0
	v_lshl_add_u64 v[14:15], s[34:35], 0, v[2:3]
	v_lshlrev_b64 v[30:31], 12, v[12:13]
	v_lshl_add_u64 v[30:31], v[14:15], 0, v[30:31]
	global_load_dword v13, v[30:31], off nt
	s_movk_i32 s34, 0x3fe
	v_cmp_gt_i32_e32 vcc, s34, v12
	v_mov_b32_e32 v30, 0
	v_mov_b32_e32 v31, 0
	s_and_saveexec_b64 s[34:35], vcc
	s_cbranch_execz .LBB0_32
	v_or_b32_e32 v32, 2, v12
	v_mov_b32_e32 v33, v3
	v_lshlrev_b64 v[32:33], 12, v[32:33]
	v_lshl_add_u64 v[32:33], v[14:15], 0, v[32:33]
	global_load_dword v31, v[32:33], off nt
.LBB0_32:
	s_or_b64 exec, exec, s[34:35]
	s_movk_i32 s34, 0x3fc
	v_cmp_gt_i32_e32 vcc, s34, v12
	s_and_saveexec_b64 s[34:35], vcc
	s_cbranch_execz .LBB0_34
	v_or_b32_e32 v32, 4, v12
	v_mov_b32_e32 v33, v3
	v_lshlrev_b64 v[32:33], 12, v[32:33]
	v_lshl_add_u64 v[32:33], v[14:15], 0, v[32:33]
	global_load_dword v30, v[32:33], off nt
.LBB0_34:
	s_or_b64 exec, exec, s[34:35]
	s_movk_i32 s34, 0x3fa
	v_cmp_gt_i32_e32 vcc, s34, v12
	v_mov_b32_e32 v32, 0
	v_mov_b32_e32 v33, 0
	s_and_saveexec_b64 s[34:35], vcc
	s_cbranch_execz .LBB0_36
	v_or_b32_e32 v34, 6, v12
	v_mov_b32_e32 v35, v3
	v_lshlrev_b64 v[34:35], 12, v[34:35]
	v_lshl_add_u64 v[34:35], v[14:15], 0, v[34:35]
	global_load_dword v33, v[34:35], off nt
.LBB0_36:
	s_or_b64 exec, exec, s[34:35]
	s_movk_i32 s34, 0x3f8
	v_cmp_gt_i32_e32 vcc, s34, v12
	s_and_saveexec_b64 s[34:35], vcc
	s_cbranch_execz .LBB0_38
	v_or_b32_e32 v34, 8, v12
	v_mov_b32_e32 v35, v3
	v_lshlrev_b64 v[34:35], 12, v[34:35]
	v_lshl_add_u64 v[34:35], v[14:15], 0, v[34:35]
	global_load_dword v32, v[34:35], off nt
.LBB0_38:
	s_or_b64 exec, exec, s[34:35]
	s_movk_i32 s34, 0x3f6
	v_cmp_gt_i32_e32 vcc, s34, v12
	v_mov_b32_e32 v34, 0
	v_mov_b32_e32 v35, 0
	s_and_saveexec_b64 s[34:35], vcc
	s_cbranch_execz .LBB0_40
	v_or_b32_e32 v36, 10, v12
	v_mov_b32_e32 v37, v3
	v_lshlrev_b64 v[36:37], 12, v[36:37]
	v_lshl_add_u64 v[36:37], v[14:15], 0, v[36:37]
	global_load_dword v35, v[36:37], off nt
.LBB0_40:
	s_or_b64 exec, exec, s[34:35]
	s_movk_i32 s34, 0x3f4
	v_cmp_gt_i32_e32 vcc, s34, v12
	s_and_saveexec_b64 s[34:35], vcc
	s_cbranch_execz .LBB0_42
	v_or_b32_e32 v36, 12, v12
	v_mov_b32_e32 v37, v3
	v_lshlrev_b64 v[36:37], 12, v[36:37]
	v_lshl_add_u64 v[36:37], v[14:15], 0, v[36:37]
	global_load_dword v34, v[36:37], off nt
.LBB0_42:
	s_or_b64 exec, exec, s[34:35]
	s_movk_i32 s34, 0x3f2
	v_cmp_gt_i32_e32 vcc, s34, v12
	v_mov_b32_e32 v36, 0
	v_mov_b32_e32 v37, 0
	s_and_saveexec_b64 s[34:35], vcc
	s_cbranch_execz .LBB0_44
	v_or_b32_e32 v38, 14, v12
	v_mov_b32_e32 v39, v3
	v_lshlrev_b64 v[38:39], 12, v[38:39]
	v_lshl_add_u64 v[38:39], v[14:15], 0, v[38:39]
	global_load_dword v37, v[38:39], off nt
.LBB0_44:
	s_or_b64 exec, exec, s[34:35]
	s_movk_i32 s34, 0x3f0
	v_cmp_gt_i32_e32 vcc, s34, v12
	s_and_saveexec_b64 s[34:35], vcc
	s_cbranch_execz .LBB0_46
	v_or_b32_e32 v38, 16, v12
	v_mov_b32_e32 v39, v3
	v_lshlrev_b64 v[38:39], 12, v[38:39]
	v_lshl_add_u64 v[38:39], v[14:15], 0, v[38:39]
	global_load_dword v36, v[38:39], off nt
.LBB0_46:
	s_or_b64 exec, exec, s[34:35]
	s_movk_i32 s34, 0x3ee
	v_cmp_gt_i32_e32 vcc, s34, v12
	v_mov_b32_e32 v38, 0
	v_mov_b32_e32 v39, 0
	s_and_saveexec_b64 s[34:35], vcc
	s_cbranch_execz .LBB0_48
	v_or_b32_e32 v40, 18, v12
	v_mov_b32_e32 v41, v3
	v_lshlrev_b64 v[40:41], 12, v[40:41]
	v_lshl_add_u64 v[40:41], v[14:15], 0, v[40:41]
	global_load_dword v39, v[40:41], off nt
.LBB0_48:
	s_or_b64 exec, exec, s[34:35]
	s_movk_i32 s34, 0x3ec
	v_cmp_gt_i32_e32 vcc, s34, v12
	s_and_saveexec_b64 s[34:35], vcc
	s_cbranch_execz .LBB0_50
	v_or_b32_e32 v40, 20, v12
	v_mov_b32_e32 v41, v3
	v_lshlrev_b64 v[40:41], 12, v[40:41]
	v_lshl_add_u64 v[40:41], v[14:15], 0, v[40:41]
	global_load_dword v38, v[40:41], off nt
.LBB0_50:
	s_or_b64 exec, exec, s[34:35]
	s_movk_i32 s34, 0x3ea
	v_cmp_gt_i32_e32 vcc, s34, v12
	v_mov_b32_e32 v40, 0
	v_mov_b32_e32 v41, 0
	s_and_saveexec_b64 s[34:35], vcc
	s_cbranch_execz .LBB0_52
	v_or_b32_e32 v42, 22, v12
	v_mov_b32_e32 v43, v3
	v_lshlrev_b64 v[42:43], 12, v[42:43]
	v_lshl_add_u64 v[42:43], v[14:15], 0, v[42:43]
	global_load_dword v41, v[42:43], off nt
.LBB0_52:
	s_or_b64 exec, exec, s[34:35]
	s_movk_i32 s34, 0x3e8
	v_cmp_gt_i32_e32 vcc, s34, v12
	s_and_saveexec_b64 s[34:35], vcc
	s_cbranch_execz .LBB0_54
	v_or_b32_e32 v42, 24, v12
	v_mov_b32_e32 v43, v3
	v_lshlrev_b64 v[42:43], 12, v[42:43]
	v_lshl_add_u64 v[42:43], v[14:15], 0, v[42:43]
	global_load_dword v40, v[42:43], off nt
.LBB0_54:
	s_or_b64 exec, exec, s[34:35]
	s_movk_i32 s34, 0x3e6
	v_cmp_gt_i32_e32 vcc, s34, v12
	v_mov_b32_e32 v42, 0
	v_mov_b32_e32 v43, 0
	s_and_saveexec_b64 s[34:35], vcc
	s_cbranch_execz .LBB0_56
	v_or_b32_e32 v44, 26, v12
	v_mov_b32_e32 v45, v3
	v_lshlrev_b64 v[44:45], 12, v[44:45]
	v_lshl_add_u64 v[44:45], v[14:15], 0, v[44:45]
	global_load_dword v43, v[44:45], off nt
.LBB0_56:
	s_or_b64 exec, exec, s[34:35]
	s_movk_i32 s34, 0x3e4
	v_cmp_gt_i32_e32 vcc, s34, v12
	s_and_saveexec_b64 s[34:35], vcc
	s_cbranch_execz .LBB0_58
	v_or_b32_e32 v44, 28, v12
	v_mov_b32_e32 v45, v3
	v_lshlrev_b64 v[44:45], 12, v[44:45]
	v_lshl_add_u64 v[44:45], v[14:15], 0, v[44:45]
	global_load_dword v42, v[44:45], off nt
; #define LAS __attribute__((address_space(3)))
; DI void tr_item8(const float* src, long src_ld, int src_col0, int kvalid, unsigned char* dst, long dst_ld, int dst_row0, int k0, float scale, LAS float* scr, int lane) {
;     float tv[32];
; #pragma unroll
;     for (int i = 0; i < 32; ++i) { const int kk = 2 * i + (lane >> 5), cc = lane & 31; tv[i] = 0.f; if ((k0 + kk) < kvalid) tv[i] = src[(size_t)(k0 + kk) * src_ld + src_col0 + cc]; }
.LBB0_58:
	s_or_b64 exec, exec, s[34:35]
	s_movk_i32 s34, 0x3e2
	v_cmp_gt_i32_e32 vcc, s34, v12
	v_mov_b32_e32 v44, 0
	v_mov_b32_e32 v45, 0
	s_and_saveexec_b64 s[34:35], vcc
	s_cbranch_execz .LBB0_60
	v_or_b32_e32 v46, 30, v12
	v_mov_b32_e32 v47, v3
	v_lshlrev_b64 v[46:47], 12, v[46:47]
	v_lshl_add_u64 v[46:47], v[14:15], 0, v[46:47]
	global_load_dword v45, v[46:47], off nt
.LBB0_60:
	s_or_b64 exec, exec, s[34:35]
	s_movk_i32 s34, 0x3e0
	v_cmp_gt_i32_e32 vcc, s34, v12
	s_and_saveexec_b64 s[34:35], vcc
	s_cbranch_execz .LBB0_62
	v_or_b32_e32 v46, 32, v12
	v_mov_b32_e32 v47, v3
	v_lshlrev_b64 v[46:47], 12, v[46:47]
	v_lshl_add_u64 v[46:47], v[14:15], 0, v[46:47]
	global_load_dword v44, v[46:47], off nt
.LBB0_62:
	s_or_b64 exec, exec, s[34:35]
	s_movk_i32 s34, 0x3de
	v_cmp_gt_i32_e32 vcc, s34, v12
	v_mov_b32_e32 v46, 0
	v_mov_b32_e32 v47, 0
	s_and_saveexec_b64 s[34:35], vcc
	s_cbranch_execz .LBB0_64
	v_or_b32_e32 v48, 34, v12
	v_mov_b32_e32 v49, v3
	v_lshlrev_b64 v[48:49], 12, v[48:49]
	v_lshl_add_u64 v[48:49], v[14:15], 0, v[48:49]
	global_load_dword v47, v[48:49], off nt
.LBB0_64:
	s_or_b64 exec, exec, s[34:35]
	s_movk_i32 s34, 0x3dc
	v_cmp_gt_i32_e32 vcc, s34, v12
	s_and_saveexec_b64 s[34:35], vcc
	s_cbranch_execz .LBB0_66
	v_or_b32_e32 v48, 36, v12
	v_mov_b32_e32 v49, v3
	v_lshlrev_b64 v[48:49], 12, v[48:49]
	v_lshl_add_u64 v[48:49], v[14:15], 0, v[48:49]
	global_load_dword v46, v[48:49], off nt
.LBB0_66:
	s_or_b64 exec, exec, s[34:35]
	s_movk_i32 s34, 0x3da
	v_cmp_gt_i32_e32 vcc, s34, v12
	v_mov_b32_e32 v48, 0
	v_mov_b32_e32 v49, 0
	s_and_saveexec_b64 s[34:35], vcc
	s_cbranch_execz .LBB0_68
	v_or_b32_e32 v50, 38, v12
	v_mov_b32_e32 v51, v3
	v_lshlrev_b64 v[50:51], 12, v[50:51]
	v_lshl_add_u64 v[50:51], v[14:15], 0, v[50:51]
	global_load_dword v49, v[50:51], off nt
.LBB0_68:
	s_or_b64 exec, exec, s[34:35]
	s_movk_i32 s34, 0x3d8
	v_cmp_gt_i32_e32 vcc, s34, v12
	s_and_saveexec_b64 s[34:35], vcc
	s_cbranch_execz .LBB0_70
	v_or_b32_e32 v50, 40, v12
	v_mov_b32_e32 v51, v3
	v_lshlrev_b64 v[50:51], 12, v[50:51]
	v_lshl_add_u64 v[50:51], v[14:15], 0, v[50:51]
	global_load_dword v48, v[50:51], off nt
.LBB0_70:
	s_or_b64 exec, exec, s[34:35]
	s_movk_i32 s34, 0x3d6
	v_cmp_gt_i32_e32 vcc, s34, v12
	v_mov_b32_e32 v50, 0
	v_mov_b32_e32 v51, 0
	s_and_saveexec_b64 s[34:35], vcc
	s_cbranch_execz .LBB0_72
	v_or_b32_e32 v52, 42, v12
	v_mov_b32_e32 v53, v3
	v_lshlrev_b64 v[52:53], 12, v[52:53]
	v_lshl_add_u64 v[52:53], v[14:15], 0, v[52:53]
	global_load_dword v51, v[52:53], off nt
.LBB0_72:
	s_or_b64 exec, exec, s[34:35]
	s_movk_i32 s34, 0x3d4
	v_cmp_gt_i32_e32 vcc, s34, v12
	s_and_saveexec_b64 s[34:35], vcc
	s_cbranch_execz .LBB0_74
	v_or_b32_e32 v52, 44, v12
	v_mov_b32_e32 v53, v3
	v_lshlrev_b64 v[52:53], 12, v[52:53]
	v_lshl_add_u64 v[52:53], v[14:15], 0, v[52:53]
	global_load_dword v50, v[52:53], off nt
.LBB0_74:
	s_or_b64 exec, exec, s[34:35]
	s_movk_i32 s34, 0x3d2
	v_cmp_gt_i32_e32 vcc, s34, v12
	v_mov_b32_e32 v52, 0
	v_mov_b32_e32 v53, 0
	s_and_saveexec_b64 s[34:35], vcc
	s_cbranch_execz .LBB0_76
	v_or_b32_e32 v54, 46, v12
	v_mov_b32_e32 v55, v3
	v_lshlrev_b64 v[54:55], 12, v[54:55]
	v_lshl_add_u64 v[54:55], v[14:15], 0, v[54:55]
	global_load_dword v53, v[54:55], off nt
.LBB0_76:
	s_or_b64 exec, exec, s[34:35]
	s_movk_i32 s34, 0x3d0
	v_cmp_gt_i32_e32 vcc, s34, v12
	s_and_saveexec_b64 s[34:35], vcc
	s_cbranch_execz .LBB0_78
	v_or_b32_e32 v54, 48, v12
	v_mov_b32_e32 v55, v3
	v_lshlrev_b64 v[54:55], 12, v[54:55]
	v_lshl_add_u64 v[54:55], v[14:15], 0, v[54:55]
	global_load_dword v52, v[54:55], off nt
.LBB0_78:
	s_or_b64 exec, exec, s[34:35]
	s_movk_i32 s34, 0x3ce
	v_cmp_gt_i32_e32 vcc, s34, v12
	v_mov_b32_e32 v54, 0
	v_mov_b32_e32 v55, 0
	s_and_saveexec_b64 s[34:35], vcc
	s_cbranch_execz .LBB0_80
	v_or_b32_e32 v56, 50, v12
	v_mov_b32_e32 v57, v3
	v_lshlrev_b64 v[56:57], 12, v[56:57]
	v_lshl_add_u64 v[56:57], v[14:15], 0, v[56:57]
	global_load_dword v55, v[56:57], off nt
.LBB0_80:
	s_or_b64 exec, exec, s[34:35]
	s_movk_i32 s34, 0x3cc
	v_cmp_gt_i32_e32 vcc, s34, v12
	s_and_saveexec_b64 s[34:35], vcc
	s_cbranch_execz .LBB0_82
	v_or_b32_e32 v56, 52, v12
	v_mov_b32_e32 v57, v3
	v_lshlrev_b64 v[56:57], 12, v[56:57]
	v_lshl_add_u64 v[56:57], v[14:15], 0, v[56:57]
	global_load_dword v54, v[56:57], off nt
.LBB0_82:
	s_or_b64 exec, exec, s[34:35]
	s_movk_i32 s34, 0x3ca
	v_cmp_gt_i32_e32 vcc, s34, v12
	v_mov_b32_e32 v56, 0
	v_mov_b32_e32 v57, 0
	s_and_saveexec_b64 s[34:35], vcc
	s_cbranch_execz .LBB0_84
	v_or_b32_e32 v58, 54, v12
	v_mov_b32_e32 v59, v3
	v_lshlrev_b64 v[58:59], 12, v[58:59]
	v_lshl_add_u64 v[58:59], v[14:15], 0, v[58:59]
	global_load_dword v57, v[58:59], off nt
.LBB0_84:
	s_or_b64 exec, exec, s[34:35]
	s_movk_i32 s34, 0x3c8
	v_cmp_gt_i32_e32 vcc, s34, v12
	s_and_saveexec_b64 s[34:35], vcc
	s_cbranch_execz .LBB0_86
	v_or_b32_e32 v58, 56, v12
	v_mov_b32_e32 v59, v3
	v_lshlrev_b64 v[58:59], 12, v[58:59]
	v_lshl_add_u64 v[58:59], v[14:15], 0, v[58:59]
	global_load_dword v56, v[58:59], off nt
.LBB0_86:
	s_or_b64 exec, exec, s[34:35]
	s_movk_i32 s34, 0x3c6
	v_cmp_gt_i32_e32 vcc, s34, v12
	v_mov_b32_e32 v58, 0
	v_mov_b32_e32 v59, 0
	s_and_saveexec_b64 s[34:35], vcc
	s_cbranch_execz .LBB0_88
	v_or_b32_e32 v60, 58, v12
	v_mov_b32_e32 v61, v3
	v_lshlrev_b64 v[60:61], 12, v[60:61]
	v_lshl_add_u64 v[60:61], v[14:15], 0, v[60:61]
	global_load_dword v59, v[60:61], off nt
.LBB0_88:
	s_or_b64 exec, exec, s[34:35]
	s_movk_i32 s34, 0x3c4
	v_cmp_gt_i32_e32 vcc, s34, v12
	s_and_saveexec_b64 s[34:35], vcc
	s_cbranch_execz .LBB0_90
	v_or_b32_e32 v60, 60, v12
	v_mov_b32_e32 v61, v3
	v_lshlrev_b64 v[60:61], 12, v[60:61]
	v_lshl_add_u64 v[60:61], v[14:15], 0, v[60:61]
	global_load_dword v58, v[60:61], off nt
.LBB0_90:
	s_or_b64 exec, exec, s[34:35]
	s_movk_i32 s34, 0x3c2
	v_cmp_gt_i32_e32 vcc, s34, v12
	v_mov_b32_e32 v60, 0
	s_and_saveexec_b64 s[34:35], vcc
	s_cbranch_execz .LBB0_92
	v_or_b32_e32 v60, 62, v12
	v_mov_b32_e32 v61, v3
	v_lshlrev_b64 v[60:61], 12, v[60:61]
	v_lshl_add_u64 v[14:15], v[14:15], 0, v[60:61]
	global_load_dword v60, v[14:15], off nt

; #define LAS __attribute__((address_space(3)))
; DI void tr_item8(const float* src, long src_ld, int src_col0, int kvalid, unsigned char* dst, long dst_ld, int dst_row0, int k0, float scale, LAS float* scr, int lane) {
;     float tv[32];
; #pragma unroll
;     for (int i = 0; i < 32; ++i) { const int kk = 2 * i + (lane >> 5), cc = lane & 31; tv[i] = 0.f; if ((k0 + kk) < kvalid) tv[i] = src[(size_t)(k0 + kk) * src_ld + src_col0 + cc]; }
; DI void phase_weights(KArgs args, LAS unsigned char* lds, const Ctx& c) {
;     ...
;         else if (r < I_IN) { const int q = r - 16 * 112, kb = q / 96, nb = q % 96;
;             if (q < 16 * 96) tr_item8(args->in[2] + (size_t)l * D * DIN, DIN, 3480 + 32 * nb, D, WSP(unsigned char, WS_WG8), D, 32 * nb, 64 * kb, 32.0f, scr, lane);
;             else { const int q2 = q - 16 * 96, kb2 = q2 / 64, nb2 = q2 % 64;
;                 tr_item8(args->in[2] + (size_t)l * D * DIN, DIN, 32 * nb2, D, WSP(unsigned char, WS_WG8), D, 3072 + 32 * nb2, 64 * kb2, 32.0f, scr, lane); }
.LBB0_100:
	s_cmpk_gt_u32 s58, 0xcff
	s_mov_b64 s[44:45], -1
	s_cbranch_scc0 .LBB0_164
	s_load_dwordx2 s[44:45], s[6:7], 0x10
	s_and_b32 s43, s58, 0x1fc0
	s_add_i32 s92, s43, 0xfffff300
	v_or_b32_e32 v15, s92, v16
	v_mul_i32_i24_e32 v30, 0x6660, v15
	s_waitcnt lgkmcnt(0)
	s_add_u32 s44, s44, s9
	s_addc_u32 s45, s45, 0
	s_and_b32 s43, s51, 0x7e0
	s_lshl_b32 s46, s43, 2
	s_add_u32 s44, s44, s46
	s_addc_u32 s45, s45, 0
	v_lshl_add_u64 v[12:13], s[44:45], 0, v[2:3]
	v_mov_b32_e32 v31, v3
	v_lshl_add_u64 v[12:13], v[12:13], 0, v[30:31]
	global_load_dword v14, v[12:13], off nt
	s_movk_i32 s44, 0x3fe
	v_cmp_gt_i32_e32 vcc, s44, v15
	v_mov_b32_e32 v30, 0
	v_mov_b32_e32 v31, 0
	s_and_saveexec_b64 s[44:45], vcc
	s_cbranch_execz .LBB0_103
	v_add_co_u32_e32 v32, vcc, 0xc000, v12
	s_nop 1
	v_addc_co_u32_e32 v33, vcc, 0, v13, vcc
	global_load_dword v31, v[32:33], off offset:3264 nt
.LBB0_103:
	s_or_b64 exec, exec, s[44:45]
	s_movk_i32 s44, 0x3fc
	v_cmp_gt_i32_e32 vcc, s44, v15
	s_and_saveexec_b64 s[44:45], vcc
	s_cbranch_execz .LBB0_105
	v_add_co_u32_e32 v32, vcc, 0x19000, v12
	s_nop 1
	v_addc_co_u32_e32 v33, vcc, 0, v13, vcc
	global_load_dword v30, v[32:33], off offset:2432 nt
.LBB0_105:
	s_or_b64 exec, exec, s[44:45]
	s_movk_i32 s44, 0x3fa
	v_cmp_gt_i32_e32 vcc, s44, v15
	v_mov_b32_e32 v32, 0
	v_mov_b32_e32 v33, 0
	s_and_saveexec_b64 s[44:45], vcc
	s_cbranch_execz .LBB0_107
	v_add_co_u32_e32 v34, vcc, 0x26000, v12
	s_nop 1
	v_addc_co_u32_e32 v35, vcc, 0, v13, vcc
	global_load_dword v33, v[34:35], off offset:1600 nt
.LBB0_107:
	s_or_b64 exec, exec, s[44:45]
	s_movk_i32 s44, 0x3f8
	v_cmp_gt_i32_e32 vcc, s44, v15
	s_and_saveexec_b64 s[44:45], vcc
	s_cbranch_execz .LBB0_109
	v_add_co_u32_e32 v34, vcc, 0x33000, v12
	s_nop 1
	v_addc_co_u32_e32 v35, vcc, 0, v13, vcc
	global_load_dword v32, v[34:35], off offset:768 nt
.LBB0_109:
	s_or_b64 exec, exec, s[44:45]
	s_movk_i32 s44, 0x3f6
	v_cmp_gt_i32_e32 vcc, s44, v15
	v_mov_b32_e32 v34, 0
	v_mov_b32_e32 v35, 0
	s_and_saveexec_b64 s[44:45], vcc
	s_cbranch_execz .LBB0_111
	v_add_co_u32_e32 v36, vcc, 0x3f000, v12
	s_nop 1
	v_addc_co_u32_e32 v37, vcc, 0, v13, vcc
	global_load_dword v35, v[36:37], off offset:4032 nt
.LBB0_111:
	s_or_b64 exec, exec, s[44:45]
	s_movk_i32 s44, 0x3f4
	v_cmp_gt_i32_e32 vcc, s44, v15
	s_and_saveexec_b64 s[44:45], vcc
	s_cbranch_execz .LBB0_113
	v_add_co_u32_e32 v36, vcc, 0x4c000, v12
	s_nop 1
	v_addc_co_u32_e32 v37, vcc, 0, v13, vcc
	global_load_dword v34, v[36:37], off offset:3200 nt
.LBB0_113:
	s_or_b64 exec, exec, s[44:45]
	s_movk_i32 s44, 0x3f2
	v_cmp_gt_i32_e32 vcc, s44, v15
	v_mov_b32_e32 v36, 0
	v_mov_b32_e32 v37, 0
	s_and_saveexec_b64 s[44:45], vcc
	s_cbranch_execz .LBB0_115
	v_add_co_u32_e32 v38, vcc, 0x59000, v12
	s_nop 1
	v_addc_co_u32_e32 v39, vcc, 0, v13, vcc
	global_load_dword v37, v[38:39], off offset:2368 nt
.LBB0_115:
	s_or_b64 exec, exec, s[44:45]
	s_movk_i32 s44, 0x3f0
	v_cmp_gt_i32_e32 vcc, s44, v15
	s_and_saveexec_b64 s[44:45], vcc
	s_cbranch_execz .LBB0_117
	v_add_co_u32_e32 v38, vcc, 0x66000, v12
	s_nop 1
	v_addc_co_u32_e32 v39, vcc, 0, v13, vcc
	global_load_dword v36, v[38:39], off offset:1536 nt
.LBB0_117:
	s_or_b64 exec, exec, s[44:45]
	s_movk_i32 s44, 0x3ee
	v_cmp_gt_i32_e32 vcc, s44, v15
	v_mov_b32_e32 v38, 0
	v_mov_b32_e32 v39, 0
	s_and_saveexec_b64 s[44:45], vcc
	s_cbranch_execz .LBB0_119
	v_add_co_u32_e32 v40, vcc, 0x73000, v12
	s_nop 1
	v_addc_co_u32_e32 v41, vcc, 0, v13, vcc
	global_load_dword v39, v[40:41], off offset:704 nt
.LBB0_119:
	s_or_b64 exec, exec, s[44:45]
	s_movk_i32 s44, 0x3ec
	v_cmp_gt_i32_e32 vcc, s44, v15
	s_and_saveexec_b64 s[44:45], vcc
	s_cbranch_execz .LBB0_121
	v_add_co_u32_e32 v40, vcc, 0x7f000, v12
	s_nop 1
	v_addc_co_u32_e32 v41, vcc, 0, v13, vcc
	global_load_dword v38, v[40:41], off offset:3968 nt
.LBB0_121:
	s_or_b64 exec, exec, s[44:45]
	s_movk_i32 s44, 0x3ea
	v_cmp_gt_i32_e32 vcc, s44, v15
	v_mov_b32_e32 v40, 0
	v_mov_b32_e32 v41, 0
	s_and_saveexec_b64 s[44:45], vcc
	s_cbranch_execz .LBB0_123
	v_add_co_u32_e32 v42, vcc, 0x8c000, v12
	s_nop 1
	v_addc_co_u32_e32 v43, vcc, 0, v13, vcc
	global_load_dword v41, v[42:43], off offset:3136 nt
.LBB0_123:
	s_or_b64 exec, exec, s[44:45]
	s_movk_i32 s44, 0x3e8
	v_cmp_gt_i32_e32 vcc, s44, v15
	s_and_saveexec_b64 s[44:45], vcc
	s_cbranch_execz .LBB0_125
	v_add_co_u32_e32 v42, vcc, 0x99000, v12
	s_nop 1
	v_addc_co_u32_e32 v43, vcc, 0, v13, vcc
	global_load_dword v40, v[42:43], off offset:2304 nt
.LBB0_125:
	s_or_b64 exec, exec, s[44:45]
	s_movk_i32 s44, 0x3e6
	v_cmp_gt_i32_e32 vcc, s44, v15
	v_mov_b32_e32 v42, 0
	v_mov_b32_e32 v43, 0
	s_and_saveexec_b64 s[44:45], vcc
	s_cbranch_execz .LBB0_127
	v_add_co_u32_e32 v44, vcc, 0xa6000, v12
	s_nop 1
	v_addc_co_u32_e32 v45, vcc, 0, v13, vcc
	global_load_dword v43, v[44:45], off offset:1472 nt
.LBB0_127:
	s_or_b64 exec, exec, s[44:45]
	s_movk_i32 s44, 0x3e4
	v_cmp_gt_i32_e32 vcc, s44, v15
	s_and_saveexec_b64 s[44:45], vcc
	s_cbranch_execz .LBB0_129
	v_add_co_u32_e32 v44, vcc, 0xb3000, v12
	s_nop 1
	v_addc_co_u32_e32 v45, vcc, 0, v13, vcc
	global_load_dword v42, v[44:45], off offset:640 nt
.LBB0_129:
	s_or_b64 exec, exec, s[44:45]
	s_movk_i32 s44, 0x3e2
	v_cmp_gt_i32_e32 vcc, s44, v15
	v_mov_b32_e32 v44, 0
	v_mov_b32_e32 v45, 0
	s_and_saveexec_b64 s[44:45], vcc
	s_cbranch_execz .LBB0_131
	v_add_co_u32_e32 v46, vcc, 0xbf000, v12
	s_nop 1
	v_addc_co_u32_e32 v47, vcc, 0, v13, vcc
	global_load_dword v45, v[46:47], off offset:3904 nt
; #define LAS __attribute__((address_space(3)))
; DI void tr_item8(const float* src, long src_ld, int src_col0, int kvalid, unsigned char* dst, long dst_ld, int dst_row0, int k0, float scale, LAS float* scr, int lane) {
;     float tv[32];
; #pragma unroll
;     for (int i = 0; i < 32; ++i) { const int kk = 2 * i + (lane >> 5), cc = lane & 31; tv[i] = 0.f; if ((k0 + kk) < kvalid) tv[i] = src[(size_t)(k0 + kk) * src_ld + src_col0 + cc]; }
.LBB0_131:
	s_or_b64 exec, exec, s[44:45]
	s_movk_i32 s44, 0x3e0
	v_cmp_gt_i32_e32 vcc, s44, v15
	s_and_saveexec_b64 s[44:45], vcc
	s_cbranch_execz .LBB0_133
	v_add_co_u32_e32 v46, vcc, 0xcc000, v12
	s_nop 1
	v_addc_co_u32_e32 v47, vcc, 0, v13, vcc
	global_load_dword v44, v[46:47], off offset:3072 nt
.LBB0_133:
	s_or_b64 exec, exec, s[44:45]
	s_movk_i32 s44, 0x3de
	v_cmp_gt_i32_e32 vcc, s44, v15
	v_mov_b32_e32 v46, 0
	v_mov_b32_e32 v47, 0
	s_and_saveexec_b64 s[44:45], vcc
	s_cbranch_execz .LBB0_135
	v_add_co_u32_e32 v48, vcc, 0xd9000, v12
	s_nop 1
	v_addc_co_u32_e32 v49, vcc, 0, v13, vcc
	global_load_dword v47, v[48:49], off offset:2240 nt
.LBB0_135:
	s_or_b64 exec, exec, s[44:45]
	s_movk_i32 s44, 0x3dc
	v_cmp_gt_i32_e32 vcc, s44, v15
	s_and_saveexec_b64 s[44:45], vcc
	s_cbranch_execz .LBB0_137
	v_add_co_u32_e32 v48, vcc, 0xe6000, v12
	s_nop 1
	v_addc_co_u32_e32 v49, vcc, 0, v13, vcc
	global_load_dword v46, v[48:49], off offset:1408 nt
.LBB0_137:
	s_or_b64 exec, exec, s[44:45]
	s_movk_i32 s44, 0x3da
	v_cmp_gt_i32_e32 vcc, s44, v15
	v_mov_b32_e32 v48, 0
	v_mov_b32_e32 v49, 0
	s_and_saveexec_b64 s[44:45], vcc
	s_cbranch_execz .LBB0_139
	v_add_co_u32_e32 v50, vcc, 0xf3000, v12
	s_nop 1
	v_addc_co_u32_e32 v51, vcc, 0, v13, vcc
	global_load_dword v49, v[50:51], off offset:576 nt
.LBB0_139:
	s_or_b64 exec, exec, s[44:45]
	s_movk_i32 s44, 0x3d8
	v_cmp_gt_i32_e32 vcc, s44, v15
	s_and_saveexec_b64 s[44:45], vcc
	s_cbranch_execz .LBB0_141
	v_add_co_u32_e32 v50, vcc, 0xff000, v12
	s_nop 1
	v_addc_co_u32_e32 v51, vcc, 0, v13, vcc
	global_load_dword v48, v[50:51], off offset:3840 nt
.LBB0_141:
	s_or_b64 exec, exec, s[44:45]
	s_movk_i32 s44, 0x3d6
	v_cmp_gt_i32_e32 vcc, s44, v15
	v_mov_b32_e32 v50, 0
	v_mov_b32_e32 v51, 0
	s_and_saveexec_b64 s[44:45], vcc
	s_cbranch_execz .LBB0_143
	v_add_co_u32_e32 v52, vcc, 0x10c000, v12
	s_nop 1
	v_addc_co_u32_e32 v53, vcc, 0, v13, vcc
	global_load_dword v51, v[52:53], off offset:3008 nt
.LBB0_143:
	s_or_b64 exec, exec, s[44:45]
	s_movk_i32 s44, 0x3d4
	v_cmp_gt_i32_e32 vcc, s44, v15
	s_and_saveexec_b64 s[44:45], vcc
	s_cbranch_execz .LBB0_145
	v_add_co_u32_e32 v52, vcc, 0x119000, v12
	s_nop 1
	v_addc_co_u32_e32 v53, vcc, 0, v13, vcc
	global_load_dword v50, v[52:53], off offset:2176 nt
.LBB0_145:
	s_or_b64 exec, exec, s[44:45]
	s_movk_i32 s44, 0x3d2
	v_cmp_gt_i32_e32 vcc, s44, v15
	v_mov_b32_e32 v52, 0
	v_mov_b32_e32 v53, 0
	s_and_saveexec_b64 s[44:45], vcc
	s_cbranch_execz .LBB0_147
	v_add_co_u32_e32 v54, vcc, 0x126000, v12
	s_nop 1
	v_addc_co_u32_e32 v55, vcc, 0, v13, vcc
	global_load_dword v53, v[54:55], off offset:1344 nt
.LBB0_147:
	s_or_b64 exec, exec, s[44:45]
	s_movk_i32 s44, 0x3d0
	v_cmp_gt_i32_e32 vcc, s44, v15
	s_and_saveexec_b64 s[44:45], vcc
	s_cbranch_execz .LBB0_149
	v_add_co_u32_e32 v54, vcc, 0x133000, v12
	s_nop 1
	v_addc_co_u32_e32 v55, vcc, 0, v13, vcc
	global_load_dword v52, v[54:55], off offset:512 nt
.LBB0_149:
	s_or_b64 exec, exec, s[44:45]
	s_movk_i32 s44, 0x3ce
	v_cmp_gt_i32_e32 vcc, s44, v15
	v_mov_b32_e32 v54, 0
	v_mov_b32_e32 v55, 0
	s_and_saveexec_b64 s[44:45], vcc
	s_cbranch_execz .LBB0_151
	v_add_co_u32_e32 v56, vcc, 0x13f000, v12
	s_nop 1
	v_addc_co_u32_e32 v57, vcc, 0, v13, vcc
	global_load_dword v55, v[56:57], off offset:3776 nt
.LBB0_151:
	s_or_b64 exec, exec, s[44:45]
	s_movk_i32 s44, 0x3cc
	v_cmp_gt_i32_e32 vcc, s44, v15
	s_and_saveexec_b64 s[44:45], vcc
	s_cbranch_execz .LBB0_153
	v_add_co_u32_e32 v56, vcc, 0x14c000, v12
	s_nop 1
	v_addc_co_u32_e32 v57, vcc, 0, v13, vcc
	global_load_dword v54, v[56:57], off offset:2944 nt
.LBB0_153:
	s_or_b64 exec, exec, s[44:45]
	s_movk_i32 s44, 0x3ca
	v_cmp_gt_i32_e32 vcc, s44, v15
	v_mov_b32_e32 v56, 0
	v_mov_b32_e32 v57, 0
	s_and_saveexec_b64 s[44:45], vcc
	s_cbranch_execz .LBB0_155
	v_add_co_u32_e32 v58, vcc, 0x159000, v12
	s_nop 1
	v_addc_co_u32_e32 v59, vcc, 0, v13, vcc
	global_load_dword v57, v[58:59], off offset:2112 nt
.LBB0_155:
	s_or_b64 exec, exec, s[44:45]
	s_movk_i32 s44, 0x3c8
	v_cmp_gt_i32_e32 vcc, s44, v15
	s_and_saveexec_b64 s[44:45], vcc
	s_cbranch_execz .LBB0_157
	v_add_co_u32_e32 v58, vcc, 0x166000, v12
	s_nop 1
	v_addc_co_u32_e32 v59, vcc, 0, v13, vcc
	global_load_dword v56, v[58:59], off offset:1280 nt
.LBB0_157:
	s_or_b64 exec, exec, s[44:45]
	s_movk_i32 s44, 0x3c6
	v_cmp_gt_i32_e32 vcc, s44, v15
	v_mov_b32_e32 v58, 0
	v_mov_b32_e32 v59, 0
	s_and_saveexec_b64 s[44:45], vcc
	s_cbranch_execz .LBB0_159
	v_add_co_u32_e32 v60, vcc, 0x173000, v12
	s_nop 1
	v_addc_co_u32_e32 v61, vcc, 0, v13, vcc
	global_load_dword v59, v[60:61], off offset:448 nt
.LBB0_159:
	s_or_b64 exec, exec, s[44:45]
	s_movk_i32 s44, 0x3c4
	v_cmp_gt_i32_e32 vcc, s44, v15
	s_and_saveexec_b64 s[44:45], vcc
	s_cbranch_execz .LBB0_161
	v_add_co_u32_e32 v60, vcc, 0x17f000, v12
	s_nop 1
	v_addc_co_u32_e32 v61, vcc, 0, v13, vcc
	global_load_dword v58, v[60:61], off offset:3712 nt
.LBB0_161:
	s_or_b64 exec, exec, s[44:45]
	s_movk_i32 s44, 0x3c2
	v_cmp_gt_i32_e32 vcc, s44, v15
	v_mov_b32_e32 v15, 0
	s_and_saveexec_b64 s[44:45], vcc
	s_cbranch_execz .LBB0_163
	v_add_co_u32_e32 v12, vcc, 0x18c000, v12
	s_nop 1
	v_addc_co_u32_e32 v13, vcc, 0, v13, vcc
	global_load_dword v15, v[12:13], off offset:2880 nt

; #define LAS __attribute__((address_space(3)))
; DI void tr_item8(const float* src, long src_ld, int src_col0, int kvalid, unsigned char* dst, long dst_ld, int dst_row0, int k0, float scale, LAS float* scr, int lane) {
;     float tv[32];
; #pragma unroll
;     for (int i = 0; i < 32; ++i) { const int kk = 2 * i + (lane >> 5), cc = lane & 31; tv[i] = 0.f; if ((k0 + kk) < kvalid) tv[i] = src[(size_t)(k0 + kk) * src_ld + src_col0 + cc]; }
; DI void phase_weights(KArgs args, LAS unsigned char* lds, const Ctx& c) {
;     ...
;         else if (r < I_IN) { const int q = r - 16 * 112, kb = q / 96, nb = q % 96;
;             if (q < 16 * 96) tr_item8(args->in[2] + (size_t)l * D * DIN, DIN, 3480 + 32 * nb, D, WSP(unsigned char, WS_WG8), D, 32 * nb, 64 * kb, 32.0f, scr, lane);
.LBB0_164:
	s_and_b64 vcc, exec, s[44:45]
	s_cbranch_vccz .LBB0_166
	s_add_i32 s43, s58, 0xf900
	s_and_b32 s44, s43, 0xffff
	s_mul_i32 s46, s44, 0xaaab
	s_load_dwordx2 s[44:45], s[6:7], 0x10
	s_lshr_b32 s47, s46, 16
	s_lshr_b32 s46, s46, 22
	s_mulk_i32 s46, 0x60
	s_sub_i32 s43, s43, s46
	s_waitcnt lgkmcnt(0)
	s_add_u32 s44, s44, s9
	s_addc_u32 s45, s45, 0
	s_lshl_b32 s43, s43, 5
	s_and_b32 s43, s43, 0xffe0
	s_and_b32 s92, s47, 0xffc0
	s_lshl_b32 s46, s43, 2
	s_add_u32 s44, s44, s46
	v_or_b32_e32 v14, s92, v16
	s_addc_u32 s45, s45, 0
	v_lshl_add_u64 v[12:13], s[44:45], 0, v[2:3]
	v_mul_u32_u24_e32 v14, 0x6660, v14
	v_mov_b32_e32 v15, v3
	v_lshl_add_u64 v[12:13], v[12:13], 0, v[14:15]
	s_movk_i32 s44, 0x3000
	v_add_co_u32_e32 v14, vcc, s44, v12
	s_mov_b32 s44, 0x10000
	s_nop 0
	v_addc_co_u32_e32 v15, vcc, 0, v13, vcc
	v_add_co_u32_e32 v30, vcc, s44, v12
	s_mov_b32 s44, 0x1c000
	s_nop 0
	v_addc_co_u32_e32 v31, vcc, 0, v13, vcc
	v_add_co_u32_e32 v32, vcc, s44, v12
	s_mov_b32 s44, 0x29000
	s_nop 0
	v_addc_co_u32_e32 v33, vcc, 0, v13, vcc
	v_add_co_u32_e32 v34, vcc, s44, v12
	s_mov_b32 s44, 0x36000
	s_nop 0
	v_addc_co_u32_e32 v35, vcc, 0, v13, vcc
	v_add_co_u32_e32 v36, vcc, s44, v12
	s_mov_b32 s44, 0x50000
	s_nop 0
	v_addc_co_u32_e32 v37, vcc, 0, v13, vcc
	v_add_co_u32_e32 v38, vcc, s69, v12
	s_nop 1
	v_addc_co_u32_e32 v39, vcc, 0, v13, vcc
	v_add_co_u32_e32 v40, vcc, s44, v12
	s_mov_b32 s44, 0x5c000
	s_nop 0
	v_addc_co_u32_e32 v41, vcc, 0, v13, vcc
	v_add_co_u32_e32 v42, vcc, s44, v12
	s_mov_b32 s44, 0x69000
	s_nop 0
	v_addc_co_u32_e32 v43, vcc, 0, v13, vcc
	v_add_co_u32_e32 v44, vcc, s44, v12
	s_mov_b32 s44, 0x76000
	s_nop 0
	v_addc_co_u32_e32 v45, vcc, 0, v13, vcc
	v_add_co_u32_e32 v46, vcc, s44, v12
	s_mov_b32 s44, 0x83000
	s_nop 0
	v_addc_co_u32_e32 v47, vcc, 0, v13, vcc
	v_add_co_u32_e32 v48, vcc, s44, v12
	s_mov_b32 s44, 0x90000
	s_nop 0
	v_addc_co_u32_e32 v49, vcc, 0, v13, vcc
	v_add_co_u32_e32 v50, vcc, s44, v12
	s_mov_b32 s44, 0x9c000
	s_nop 0
	v_addc_co_u32_e32 v51, vcc, 0, v13, vcc
	v_add_co_u32_e32 v52, vcc, s44, v12
	s_mov_b32 s44, 0xa9000
	s_nop 0
	v_addc_co_u32_e32 v53, vcc, 0, v13, vcc
	v_add_co_u32_e32 v54, vcc, s44, v12
	s_mov_b32 s44, 0xb6000
	s_nop 0
	v_addc_co_u32_e32 v55, vcc, 0, v13, vcc
	v_add_co_u32_e32 v56, vcc, s44, v12
	s_mov_b32 s44, 0xc3000
	s_nop 0
	v_addc_co_u32_e32 v57, vcc, 0, v13, vcc
	v_add_co_u32_e32 v58, vcc, s44, v12
	s_mov_b32 s44, 0xd0000
	s_nop 0
	v_addc_co_u32_e32 v59, vcc, 0, v13, vcc
	v_add_co_u32_e32 v60, vcc, s44, v12
	s_mov_b32 s44, 0xdc000
	s_nop 0
	v_addc_co_u32_e32 v61, vcc, 0, v13, vcc
	v_add_co_u32_e32 v62, vcc, s44, v12
	s_mov_b32 s44, 0xe9000
	s_nop 0
	v_addc_co_u32_e32 v63, vcc, 0, v13, vcc
	v_add_co_u32_e32 v64, vcc, s44, v12
	s_mov_b32 s44, 0xf6000
	s_nop 0
	v_addc_co_u32_e32 v65, vcc, 0, v13, vcc
	v_add_co_u32_e32 v66, vcc, s44, v12
	s_mov_b32 s44, 0x103000
	s_nop 0
	v_addc_co_u32_e32 v67, vcc, 0, v13, vcc
	v_add_co_u32_e32 v68, vcc, s44, v12
	s_mov_b32 s44, 0x110000
	s_nop 0
	v_addc_co_u32_e32 v69, vcc, 0, v13, vcc
	v_add_co_u32_e32 v70, vcc, s44, v12
	s_mov_b32 s44, 0x11c000
	s_nop 0
	v_addc_co_u32_e32 v71, vcc, 0, v13, vcc
	v_add_co_u32_e32 v72, vcc, s44, v12
	s_mov_b32 s44, 0x129000
	s_nop 0
	v_addc_co_u32_e32 v73, vcc, 0, v13, vcc
	v_add_co_u32_e32 v74, vcc, s44, v12
	s_mov_b32 s44, 0x136000
	s_nop 0
	v_addc_co_u32_e32 v75, vcc, 0, v13, vcc
	v_add_co_u32_e32 v76, vcc, s44, v12
	s_mov_b32 s44, 0x143000
	s_nop 0
	v_addc_co_u32_e32 v77, vcc, 0, v13, vcc
	v_add_co_u32_e32 v78, vcc, s44, v12
	s_mov_b32 s44, 0x150000
	s_nop 0
	v_addc_co_u32_e32 v79, vcc, 0, v13, vcc
	v_add_co_u32_e32 v80, vcc, s44, v12
	s_mov_b32 s44, 0x15c000
	s_nop 0
	v_addc_co_u32_e32 v81, vcc, 0, v13, vcc
	v_add_co_u32_e32 v82, vcc, s44, v12
	s_mov_b32 s44, 0x169000
	s_nop 0
	v_addc_co_u32_e32 v83, vcc, 0, v13, vcc
	v_add_co_u32_e32 v84, vcc, s44, v12
	s_mov_b32 s44, 0x176000
	s_nop 0
	v_addc_co_u32_e32 v85, vcc, 0, v13, vcc
	v_add_co_u32_e32 v86, vcc, s44, v12
	s_mov_b32 s44, 0x183000
	s_nop 0
	v_addc_co_u32_e32 v87, vcc, 0, v13, vcc
	v_add_co_u32_e32 v88, vcc, s44, v12
	s_mov_b32 s44, 0x190000
	s_nop 0
	v_addc_co_u32_e32 v89, vcc, 0, v13, vcc
	v_add_co_u32_e32 v12, vcc, s44, v12
	s_nop 1
	v_addc_co_u32_e32 v13, vcc, 0, v13, vcc
	global_load_dword v14, v[14:15], off offset:1632 nt
	s_nop 0
	global_load_dword v15, v[30:31], off offset:800 nt
	s_nop 0
	global_load_dword v30, v[32:33], off offset:4064 nt
	global_load_dword v31, v[34:35], off offset:3232 nt
	s_nop 0
	global_load_dword v32, v[36:37], off offset:2400 nt
	global_load_dword v33, v[38:39], off offset:1568 nt
	global_load_dword v34, v[40:41], off offset:736 nt
	global_load_dword v35, v[42:43], off offset:4000 nt
	s_nop 0
	global_load_dword v36, v[44:45], off offset:3168 nt
	global_load_dword v37, v[46:47], off offset:2336 nt
	global_load_dword v38, v[48:49], off offset:1504 nt
	global_load_dword v39, v[50:51], off offset:672 nt
	global_load_dword v40, v[52:53], off offset:3936 nt
	global_load_dword v41, v[54:55], off offset:3104 nt
	global_load_dword v42, v[56:57], off offset:2272 nt
	global_load_dword v43, v[58:59], off offset:1440 nt
	global_load_dword v44, v[60:61], off offset:608 nt
	global_load_dword v45, v[62:63], off offset:3872 nt
	global_load_dword v46, v[64:65], off offset:3040 nt
	global_load_dword v47, v[66:67], off offset:2208 nt
	global_load_dword v48, v[68:69], off offset:1376 nt
	global_load_dword v49, v[70:71], off offset:544 nt
	global_load_dword v50, v[72:73], off offset:3808 nt
	global_load_dword v51, v[74:75], off offset:2976 nt
	global_load_dword v52, v[76:77], off offset:2144 nt
	global_load_dword v53, v[78:79], off offset:1312 nt
	global_load_dword v54, v[80:81], off offset:480 nt
	global_load_dword v55, v[82:83], off offset:3744 nt
	global_load_dword v56, v[84:85], off offset:2912 nt
	global_load_dword v57, v[86:87], off offset:2080 nt
	global_load_dword v58, v[88:89], off offset:1248 nt
	s_nop 0
	global_load_dword v12, v[12:13], off offset:416 nt
	s_waitcnt vmcnt(0)
; #define LAS __attribute__((address_space(3)))
; DI void tr_item8(const float* src, long src_ld, int src_col0, int kvalid, unsigned char* dst, long dst_ld, int dst_row0, int k0, float scale, LAS float* scr, int lane) {
;     ...
; #pragma unroll
;     for (int i = 0; i < 32; ++i) { const int kk = 2 * i + (lane >> 5), cc = lane & 31; scr[kk * 33 + cc] = tv[i]; }
;     asm volatile("s_waitcnt lgkmcnt(0)" ::: "memory");
;     const int c8 = lane & 7;
; #pragma unroll
;     for (int j = 0; j < 4; ++j) { const int n = (lane >> 3) + 8 * j; const LAS float* s = scr + (8 * c8) * 33 + n;
;         u32x2 o; o.x = pk4_fp8(s[0 * 33] * scale, s[1 * 33] * scale, s[2 * 33] * scale, s[3 * 33] * scale); o.y = pk4_fp8(s[4 * 33] * scale, s[5 * 33] * scale, s[6 * 33] * scale, s[7 * 33] * scale);
;         *(u32x2*)(dst + (size_t)(dst_row0 + n) * dst_ld + k0 + 8 * c8) = o; }
;     asm volatile("s_waitcnt lgkmcnt(0)" ::: "memory");
	ds_write2_b32 v17, v14, v15 offset1:66
	s_waitcnt vmcnt(28)
	ds_write2_b32 v17, v30, v31 offset0:132 offset1:198
	s_waitcnt vmcnt(26)
	ds_write2_b32 v23, v32, v33 offset0:8 offset1:74
	s_waitcnt vmcnt(24)
	ds_write2_b32 v23, v34, v35 offset0:140 offset1:206
	s_waitcnt vmcnt(22)
	ds_write2_b32 v24, v36, v37 offset0:16 offset1:82
	s_waitcnt vmcnt(20)
	ds_write2_b32 v24, v38, v39 offset0:148 offset1:214
	s_waitcnt vmcnt(18)
	ds_write2_b32 v25, v40, v41 offset0:24 offset1:90
	s_waitcnt vmcnt(16)
	ds_write2_b32 v25, v42, v43 offset0:156 offset1:222
	s_waitcnt vmcnt(14)
	ds_write2_b32 v26, v44, v45 offset0:32 offset1:98
	s_waitcnt vmcnt(12)
	ds_write2_b32 v26, v46, v47 offset0:164 offset1:230
	s_waitcnt vmcnt(10)
	ds_write2_b32 v27, v48, v49 offset0:40 offset1:106
	s_waitcnt vmcnt(8)
	ds_write2_b32 v27, v50, v51 offset0:172 offset1:238
	s_waitcnt vmcnt(6)
	ds_write2_b32 v28, v52, v53 offset0:48 offset1:114
	s_waitcnt vmcnt(4)
	ds_write2_b32 v28, v54, v55 offset0:180 offset1:246
	s_waitcnt vmcnt(2)
	ds_write2_b32 v29, v56, v57 offset0:56 offset1:122
	s_waitcnt vmcnt(0)
	ds_write2_b32 v29, v58, v12 offset0:188 offset1:254
	s_waitcnt lgkmcnt(0)
	ds_read2_b32 v[12:13], v19 offset1:8
	ds_read2_b32 v[14:15], v19 offset0:33 offset1:41
	ds_read2_b32 v[30:31], v19 offset0:66 offset1:74
	ds_read2_b32 v[34:35], v19 offset0:99 offset1:107
	ds_read2_b32 v[36:37], v19 offset0:132 offset1:140
	ds_read2_b32 v[38:39], v19 offset0:165 offset1:173
	s_waitcnt lgkmcnt(5)
	v_mul_f32_e32 v12, 0x42000000, v12
	s_waitcnt lgkmcnt(4)
	v_mul_f32_e32 v14, 0x42000000, v14
	v_mov_b32_e32 v40, v3
	ds_read2_b32 v[42:43], v19 offset0:198 offset1:206
	ds_read2_b32 v[44:45], v19 offset0:231 offset1:239
	v_cvt_pk_fp8_f32 v40, v12, v14
	s_waitcnt lgkmcnt(3)
	v_mul_f32_e32 v12, 0x42000000, v36
	s_waitcnt lgkmcnt(2)
	v_mul_f32_e32 v14, 0x42000000, v38
	v_mov_b32_e32 v41, v3
	v_cvt_pk_fp8_f32 v41, v12, v14
	s_waitcnt lgkmcnt(1)
	v_mul_f32_e32 v12, 0x42000000, v42
	s_waitcnt lgkmcnt(0)
	v_mul_f32_e32 v14, 0x42000000, v44
	v_mul_f32_e32 v13, 0x42000000, v13
	v_cvt_pk_fp8_f32 v41, v12, v14 op_sel:[0,0,1]
	v_or_b32_e32 v12, s43, v18
	v_lshlrev_b32_e32 v46, 10, v12
	v_mul_f32_e32 v14, 0x42000000, v15
	v_mov_b32_e32 v12, v3
	v_mul_f32_e32 v15, 0x42000000, v31
	v_cvt_pk_fp8_f32 v12, v13, v14
	v_mul_f32_e32 v14, 0x42000000, v37
	v_mul_f32_e32 v31, 0x42000000, v39
	v_mov_b32_e32 v13, v3
	v_cvt_pk_fp8_f32 v13, v14, v31
	v_mul_f32_e32 v30, 0x42000000, v30
	v_mul_f32_e32 v34, 0x42000000, v34
	v_cvt_pk_fp8_f32 v40, v30, v34 op_sel:[0,0,1]
	v_mul_f32_e32 v30, 0x42000000, v35
	v_cvt_pk_fp8_f32 v12, v15, v30 op_sel:[0,0,1]
	v_mul_f32_e32 v14, 0x42000000, v43
	v_mul_f32_e32 v15, 0x42000000, v45
	v_cvt_pk_fp8_f32 v13, v14, v15 op_sel:[0,0,1]
	v_lshl_add_u64 v[32:33], v[10:11], 0, s[92:93]
	v_mov_b32_e32 v47, v3
	v_or_b32_e32 v14, s43, v20
	v_lshl_add_u64 v[46:47], v[32:33], 0, v[46:47]
	v_lshlrev_b32_e32 v14, 10, v14
	v_mov_b32_e32 v15, v3
	global_store_dwordx2 v[46:47], v[40:41], off
	v_lshl_add_u64 v[14:15], v[32:33], 0, v[14:15]
	ds_read2_b32 v[30:31], v19 offset0:16 offset1:24
	ds_read2_b32 v[34:35], v19 offset0:49 offset1:57
	ds_read2_b32 v[36:37], v19 offset0:82 offset1:90
	global_store_dwordx2 v[14:15], v[12:13], off
	ds_read2_b32 v[12:13], v19 offset0:115 offset1:123
	ds_read2_b32 v[14:15], v19 offset0:148 offset1:156
	ds_read2_b32 v[38:39], v19 offset0:181 offset1:189
	s_waitcnt lgkmcnt(5)
	v_mul_f32_e32 v30, 0x42000000, v30
	s_waitcnt lgkmcnt(4)
	v_mul_f32_e32 v34, 0x42000000, v34
	v_mov_b32_e32 v40, v3
	ds_read2_b32 v[42:43], v19 offset0:214 offset1:222
	ds_read2_b32 v[44:45], v19 offset0:247 offset1:255
	v_cvt_pk_fp8_f32 v40, v30, v34
	s_waitcnt lgkmcnt(3)
	v_mul_f32_e32 v14, 0x42000000, v14
	s_waitcnt lgkmcnt(2)
	v_mul_f32_e32 v30, 0x42000000, v38
	v_mov_b32_e32 v41, v3
	v_cvt_pk_fp8_f32 v41, v14, v30
	v_mul_f32_e32 v36, 0x42000000, v36
	v_mul_f32_e32 v12, 0x42000000, v12
	v_cvt_pk_fp8_f32 v40, v36, v12 op_sel:[0,0,1]
	s_waitcnt lgkmcnt(1)
	v_mul_f32_e32 v12, 0x42000000, v42
	s_waitcnt lgkmcnt(0)
	v_mul_f32_e32 v14, 0x42000000, v44
	v_cvt_pk_fp8_f32 v41, v12, v14 op_sel:[0,0,1]
	v_or_b32_e32 v12, s43, v21
	v_lshlrev_b32_e32 v46, 10, v12
	v_mul_f32_e32 v14, 0x42000000, v31
	v_mul_f32_e32 v30, 0x42000000, v35
	v_mov_b32_e32 v12, v3
	v_mul_f32_e32 v34, 0x42000000, v13
	v_cvt_pk_fp8_f32 v12, v14, v30
	v_mul_f32_e32 v14, 0x42000000, v15
	v_mul_f32_e32 v15, 0x42000000, v39
	v_mov_b32_e32 v13, v3
	v_cvt_pk_fp8_f32 v13, v14, v15
	v_mul_f32_e32 v31, 0x42000000, v37
	v_mul_f32_e32 v14, 0x42000000, v43
	v_mul_f32_e32 v15, 0x42000000, v45
	v_cvt_pk_fp8_f32 v12, v31, v34 op_sel:[0,0,1]
	v_cvt_pk_fp8_f32 v13, v14, v15 op_sel:[0,0,1]
	v_or_b32_e32 v14, s43, v22
	v_mov_b32_e32 v47, v3
	v_lshlrev_b32_e32 v14, 10, v14
	v_mov_b32_e32 v15, v3
	v_lshl_add_u64 v[46:47], v[32:33], 0, v[46:47]
	v_lshl_add_u64 v[14:15], v[32:33], 0, v[14:15]
	global_store_dwordx2 v[46:47], v[40:41], off
	global_store_dwordx2 v[14:15], v[12:13], off
	s_waitcnt lgkmcnt(0)

; #define LAS __attribute__((address_space(3)))
; DI void tr_item(const float* src, long src_ld, int src_col0, int nvalid, int kvalid, bf16_t* dst, long dst_ld, int dst_row0, int k0, LAS float* scr, int lane) {
;     float tv[32];
; #pragma unroll
;     for (int i = 0; i < 32; ++i) { const int kk = 2 * i + (lane >> 5), cc = lane & 31;
;         tv[i] = 0.f; if ((k0 + kk) < kvalid && cc < nvalid) tv[i] = src[(size_t)(k0 + kk) * src_ld + src_col0 + cc]; }
.LBB0_170:
	s_ashr_i32 s43, s42, 31
	s_lshl_b64 s[40:41], s[42:43], 2
	v_add_u32_e32 v14, s34, v16
	s_add_u32 s38, s38, s40
	s_addc_u32 s39, s39, s41
	v_cmp_gt_i32_e32 vcc, s35, v14
	v_lshl_add_u64 v[12:13], s[38:39], 0, v[2:3]
	s_and_b64 s[40:41], vcc, s[30:31]
	v_mov_b32_e32 v15, 0
	v_mov_b32_e32 v30, 0
	s_and_saveexec_b64 s[38:39], s[40:41]
	s_cbranch_execz .LBB0_172
	v_mad_i64_i32 v[30:31], s[40:41], s46, v14, 0
	v_lshl_add_u64 v[30:31], v[30:31], 2, v[12:13]
	global_load_dword v30, v[30:31], off nt
.LBB0_172:
	s_or_b64 exec, exec, s[38:39]
	v_add_u32_e32 v31, 2, v14
	v_cmp_gt_i32_e32 vcc, s35, v31
	s_and_b64 s[40:41], vcc, s[30:31]
	s_and_saveexec_b64 s[38:39], s[40:41]
	s_cbranch_execz .LBB0_174
	v_mad_i64_i32 v[32:33], s[40:41], s46, v31, 0
	v_lshl_add_u64 v[32:33], v[32:33], 2, v[12:13]
	global_load_dword v15, v[32:33], off nt
.LBB0_174:
	s_or_b64 exec, exec, s[38:39]
	v_add_u32_e32 v33, 4, v14
	v_cmp_gt_i32_e32 vcc, s35, v33
	s_and_b64 s[40:41], vcc, s[30:31]
	v_mov_b32_e32 v31, 0
	v_mov_b32_e32 v32, 0
	s_and_saveexec_b64 s[38:39], s[40:41]
	s_cbranch_execz .LBB0_176
	v_mad_i64_i32 v[32:33], s[40:41], s46, v33, 0
	v_lshl_add_u64 v[32:33], v[32:33], 2, v[12:13]
	global_load_dword v32, v[32:33], off nt
.LBB0_176:
	s_or_b64 exec, exec, s[38:39]
	v_add_u32_e32 v33, 6, v14
	v_cmp_gt_i32_e32 vcc, s35, v33
	s_and_b64 s[40:41], vcc, s[30:31]
	s_and_saveexec_b64 s[38:39], s[40:41]
	s_cbranch_execz .LBB0_178
	v_mad_i64_i32 v[34:35], s[40:41], s46, v33, 0
	v_lshl_add_u64 v[34:35], v[34:35], 2, v[12:13]
	global_load_dword v31, v[34:35], off nt
.LBB0_178:
	s_or_b64 exec, exec, s[38:39]
	v_add_u32_e32 v35, 8, v14
	v_cmp_gt_i32_e32 vcc, s35, v35
	s_and_b64 s[40:41], vcc, s[30:31]
	v_mov_b32_e32 v33, 0
	v_mov_b32_e32 v34, 0
	s_and_saveexec_b64 s[38:39], s[40:41]
	s_cbranch_execz .LBB0_180
	v_mad_i64_i32 v[34:35], s[40:41], s46, v35, 0
	v_lshl_add_u64 v[34:35], v[34:35], 2, v[12:13]
	global_load_dword v34, v[34:35], off nt
.LBB0_180:
	s_or_b64 exec, exec, s[38:39]
	v_add_u32_e32 v35, 10, v14
	v_cmp_gt_i32_e32 vcc, s35, v35
	s_and_b64 s[40:41], vcc, s[30:31]
	s_and_saveexec_b64 s[38:39], s[40:41]
	s_cbranch_execz .LBB0_182
	v_mad_i64_i32 v[36:37], s[40:41], s46, v35, 0
	v_lshl_add_u64 v[36:37], v[36:37], 2, v[12:13]
	global_load_dword v33, v[36:37], off nt
.LBB0_182:
	s_or_b64 exec, exec, s[38:39]
	v_add_u32_e32 v37, 12, v14
	v_cmp_gt_i32_e32 vcc, s35, v37
	s_and_b64 s[40:41], vcc, s[30:31]
	v_mov_b32_e32 v35, 0
	v_mov_b32_e32 v36, 0
	s_and_saveexec_b64 s[38:39], s[40:41]
	s_cbranch_execz .LBB0_184
	v_mad_i64_i32 v[36:37], s[40:41], s46, v37, 0
	v_lshl_add_u64 v[36:37], v[36:37], 2, v[12:13]
	global_load_dword v36, v[36:37], off nt
.LBB0_184:
	s_or_b64 exec, exec, s[38:39]
	v_add_u32_e32 v37, 14, v14
	v_cmp_gt_i32_e32 vcc, s35, v37
	s_and_b64 s[40:41], vcc, s[30:31]
	s_and_saveexec_b64 s[38:39], s[40:41]
	s_cbranch_execz .LBB0_186
	v_mad_i64_i32 v[38:39], s[40:41], s46, v37, 0
	v_lshl_add_u64 v[38:39], v[38:39], 2, v[12:13]
	global_load_dword v35, v[38:39], off nt
.LBB0_186:
	s_or_b64 exec, exec, s[38:39]
	v_add_u32_e32 v39, 16, v14
	v_cmp_gt_i32_e32 vcc, s35, v39
	s_and_b64 s[40:41], vcc, s[30:31]
	v_mov_b32_e32 v37, 0
	v_mov_b32_e32 v38, 0
	s_and_saveexec_b64 s[38:39], s[40:41]
	s_cbranch_execz .LBB0_188
	v_mad_i64_i32 v[38:39], s[40:41], s46, v39, 0
	v_lshl_add_u64 v[38:39], v[38:39], 2, v[12:13]
	global_load_dword v38, v[38:39], off nt
.LBB0_188:
	s_or_b64 exec, exec, s[38:39]
	v_add_u32_e32 v39, 18, v14
	v_cmp_gt_i32_e32 vcc, s35, v39
	s_and_b64 s[40:41], vcc, s[30:31]
	s_and_saveexec_b64 s[38:39], s[40:41]
	s_cbranch_execz .LBB0_190
	v_mad_i64_i32 v[40:41], s[40:41], s46, v39, 0
	v_lshl_add_u64 v[40:41], v[40:41], 2, v[12:13]
	global_load_dword v37, v[40:41], off nt
.LBB0_190:
	s_or_b64 exec, exec, s[38:39]
	v_add_u32_e32 v41, 20, v14
	v_cmp_gt_i32_e32 vcc, s35, v41
	s_and_b64 s[40:41], vcc, s[30:31]
	v_mov_b32_e32 v39, 0
	v_mov_b32_e32 v40, 0
	s_and_saveexec_b64 s[38:39], s[40:41]
	s_cbranch_execz .LBB0_192
	v_mad_i64_i32 v[40:41], s[40:41], s46, v41, 0
	v_lshl_add_u64 v[40:41], v[40:41], 2, v[12:13]
	global_load_dword v40, v[40:41], off nt
.LBB0_192:
	s_or_b64 exec, exec, s[38:39]
	v_add_u32_e32 v41, 22, v14
	v_cmp_gt_i32_e32 vcc, s35, v41
	s_and_b64 s[40:41], vcc, s[30:31]
	s_and_saveexec_b64 s[38:39], s[40:41]
	s_cbranch_execz .LBB0_194
	v_mad_i64_i32 v[42:43], s[40:41], s46, v41, 0
	v_lshl_add_u64 v[42:43], v[42:43], 2, v[12:13]
	global_load_dword v39, v[42:43], off nt
.LBB0_194:
	s_or_b64 exec, exec, s[38:39]
	v_add_u32_e32 v43, 24, v14
	v_cmp_gt_i32_e32 vcc, s35, v43
	s_and_b64 s[40:41], vcc, s[30:31]
	v_mov_b32_e32 v41, 0
	v_mov_b32_e32 v42, 0
	s_and_saveexec_b64 s[38:39], s[40:41]
	s_cbranch_execz .LBB0_196
	v_mad_i64_i32 v[42:43], s[40:41], s46, v43, 0
	v_lshl_add_u64 v[42:43], v[42:43], 2, v[12:13]
	global_load_dword v42, v[42:43], off nt
.LBB0_196:
	s_or_b64 exec, exec, s[38:39]
	v_add_u32_e32 v43, 26, v14
	v_cmp_gt_i32_e32 vcc, s35, v43
	s_and_b64 s[40:41], vcc, s[30:31]
	s_and_saveexec_b64 s[38:39], s[40:41]
	s_cbranch_execz .LBB0_198
	v_mad_i64_i32 v[44:45], s[40:41], s46, v43, 0
	v_lshl_add_u64 v[44:45], v[44:45], 2, v[12:13]
	global_load_dword v41, v[44:45], off nt
.LBB0_198:
	s_or_b64 exec, exec, s[38:39]
	v_add_u32_e32 v45, 28, v14
	v_cmp_gt_i32_e32 vcc, s35, v45
	s_and_b64 s[40:41], vcc, s[30:31]
	v_mov_b32_e32 v43, 0
	v_mov_b32_e32 v44, 0
	s_and_saveexec_b64 s[38:39], s[40:41]
	s_cbranch_execz .LBB0_200
	v_mad_i64_i32 v[44:45], s[40:41], s46, v45, 0
	v_lshl_add_u64 v[44:45], v[44:45], 2, v[12:13]
	global_load_dword v44, v[44:45], off nt
; #define LAS __attribute__((address_space(3)))
; DI void tr_item(const float* src, long src_ld, int src_col0, int nvalid, int kvalid, bf16_t* dst, long dst_ld, int dst_row0, int k0, LAS float* scr, int lane) {
;     float tv[32];
; #pragma unroll
;     for (int i = 0; i < 32; ++i) { const int kk = 2 * i + (lane >> 5), cc = lane & 31;
;         tv[i] = 0.f; if ((k0 + kk) < kvalid && cc < nvalid) tv[i] = src[(size_t)(k0 + kk) * src_ld + src_col0 + cc]; }
.LBB0_200:
	s_or_b64 exec, exec, s[38:39]
	v_add_u32_e32 v45, 30, v14
	v_cmp_gt_i32_e32 vcc, s35, v45
	s_and_b64 s[40:41], vcc, s[30:31]
	s_and_saveexec_b64 s[38:39], s[40:41]
	s_cbranch_execz .LBB0_202
	v_mad_i64_i32 v[46:47], s[40:41], s46, v45, 0
	v_lshl_add_u64 v[46:47], v[46:47], 2, v[12:13]
	global_load_dword v43, v[46:47], off nt
.LBB0_202:
	s_or_b64 exec, exec, s[38:39]
	v_add_u32_e32 v47, 32, v14
	v_cmp_gt_i32_e32 vcc, s35, v47
	s_and_b64 s[40:41], vcc, s[30:31]
	v_mov_b32_e32 v45, 0
	v_mov_b32_e32 v46, 0
	s_and_saveexec_b64 s[38:39], s[40:41]
	s_cbranch_execz .LBB0_204
	v_mad_i64_i32 v[46:47], s[40:41], s46, v47, 0
	v_lshl_add_u64 v[46:47], v[46:47], 2, v[12:13]
	global_load_dword v46, v[46:47], off nt
.LBB0_204:
	s_or_b64 exec, exec, s[38:39]
	v_add_u32_e32 v47, 34, v14
	v_cmp_gt_i32_e32 vcc, s35, v47
	s_and_b64 s[40:41], vcc, s[30:31]
	s_and_saveexec_b64 s[38:39], s[40:41]
	s_cbranch_execz .LBB0_206
	v_mad_i64_i32 v[48:49], s[40:41], s46, v47, 0
	v_lshl_add_u64 v[48:49], v[48:49], 2, v[12:13]
	global_load_dword v45, v[48:49], off nt
.LBB0_206:
	s_or_b64 exec, exec, s[38:39]
	v_add_u32_e32 v49, 36, v14
	v_cmp_gt_i32_e32 vcc, s35, v49
	s_and_b64 s[40:41], vcc, s[30:31]
	v_mov_b32_e32 v47, 0
	v_mov_b32_e32 v48, 0
	s_and_saveexec_b64 s[38:39], s[40:41]
	s_cbranch_execz .LBB0_208
	v_mad_i64_i32 v[48:49], s[40:41], s46, v49, 0
	v_lshl_add_u64 v[48:49], v[48:49], 2, v[12:13]
	global_load_dword v48, v[48:49], off nt
.LBB0_208:
	s_or_b64 exec, exec, s[38:39]
	v_add_u32_e32 v49, 38, v14
	v_cmp_gt_i32_e32 vcc, s35, v49
	s_and_b64 s[40:41], vcc, s[30:31]
	s_and_saveexec_b64 s[38:39], s[40:41]
	s_cbranch_execz .LBB0_210
	v_mad_i64_i32 v[50:51], s[40:41], s46, v49, 0
	v_lshl_add_u64 v[50:51], v[50:51], 2, v[12:13]
	global_load_dword v47, v[50:51], off nt
.LBB0_210:
	s_or_b64 exec, exec, s[38:39]
	v_add_u32_e32 v51, 40, v14
	v_cmp_gt_i32_e32 vcc, s35, v51
	s_and_b64 s[40:41], vcc, s[30:31]
	v_mov_b32_e32 v49, 0
	v_mov_b32_e32 v50, 0
	s_and_saveexec_b64 s[38:39], s[40:41]
	s_cbranch_execz .LBB0_212
	v_mad_i64_i32 v[50:51], s[40:41], s46, v51, 0
	v_lshl_add_u64 v[50:51], v[50:51], 2, v[12:13]
	global_load_dword v50, v[50:51], off nt
.LBB0_212:
	s_or_b64 exec, exec, s[38:39]
	v_add_u32_e32 v51, 42, v14
	v_cmp_gt_i32_e32 vcc, s35, v51
	s_and_b64 s[40:41], vcc, s[30:31]
	s_and_saveexec_b64 s[38:39], s[40:41]
	s_cbranch_execz .LBB0_214
	v_mad_i64_i32 v[52:53], s[40:41], s46, v51, 0
	v_lshl_add_u64 v[52:53], v[52:53], 2, v[12:13]
	global_load_dword v49, v[52:53], off nt
.LBB0_214:
	s_or_b64 exec, exec, s[38:39]
	v_add_u32_e32 v53, 44, v14
	v_cmp_gt_i32_e32 vcc, s35, v53
	s_and_b64 s[40:41], vcc, s[30:31]
	v_mov_b32_e32 v51, 0
	v_mov_b32_e32 v52, 0
	s_and_saveexec_b64 s[38:39], s[40:41]
	s_cbranch_execz .LBB0_216
	v_mad_i64_i32 v[52:53], s[40:41], s46, v53, 0
	v_lshl_add_u64 v[52:53], v[52:53], 2, v[12:13]
	global_load_dword v52, v[52:53], off nt
.LBB0_216:
	s_or_b64 exec, exec, s[38:39]
	v_add_u32_e32 v53, 46, v14
	v_cmp_gt_i32_e32 vcc, s35, v53
	s_and_b64 s[40:41], vcc, s[30:31]
	s_and_saveexec_b64 s[38:39], s[40:41]
	s_cbranch_execz .LBB0_218
	v_mad_i64_i32 v[54:55], s[40:41], s46, v53, 0
	v_lshl_add_u64 v[54:55], v[54:55], 2, v[12:13]
	global_load_dword v51, v[54:55], off nt
.LBB0_218:
	s_or_b64 exec, exec, s[38:39]
	v_add_u32_e32 v55, 48, v14
	v_cmp_gt_i32_e32 vcc, s35, v55
	s_and_b64 s[40:41], vcc, s[30:31]
	v_mov_b32_e32 v53, 0
	v_mov_b32_e32 v54, 0
	s_and_saveexec_b64 s[38:39], s[40:41]
	s_cbranch_execz .LBB0_220
	v_mad_i64_i32 v[54:55], s[40:41], s46, v55, 0
	v_lshl_add_u64 v[54:55], v[54:55], 2, v[12:13]
	global_load_dword v54, v[54:55], off nt
.LBB0_220:
	s_or_b64 exec, exec, s[38:39]
	v_add_u32_e32 v55, 50, v14
	v_cmp_gt_i32_e32 vcc, s35, v55
	s_and_b64 s[40:41], vcc, s[30:31]
	s_and_saveexec_b64 s[38:39], s[40:41]
	s_cbranch_execz .LBB0_222
	v_mad_i64_i32 v[56:57], s[40:41], s46, v55, 0
	v_lshl_add_u64 v[56:57], v[56:57], 2, v[12:13]
	global_load_dword v53, v[56:57], off nt
.LBB0_222:
	s_or_b64 exec, exec, s[38:39]
	v_add_u32_e32 v57, 52, v14
	v_cmp_gt_i32_e32 vcc, s35, v57
	s_and_b64 s[40:41], vcc, s[30:31]
	v_mov_b32_e32 v55, 0
	v_mov_b32_e32 v56, 0
	s_and_saveexec_b64 s[38:39], s[40:41]
	s_cbranch_execz .LBB0_224
	v_mad_i64_i32 v[56:57], s[40:41], s46, v57, 0
	v_lshl_add_u64 v[56:57], v[56:57], 2, v[12:13]
	global_load_dword v56, v[56:57], off nt
.LBB0_224:
	s_or_b64 exec, exec, s[38:39]
	v_add_u32_e32 v57, 54, v14
	v_cmp_gt_i32_e32 vcc, s35, v57
	s_and_b64 s[40:41], vcc, s[30:31]
	s_and_saveexec_b64 s[38:39], s[40:41]
	s_cbranch_execz .LBB0_226
	v_mad_i64_i32 v[58:59], s[40:41], s46, v57, 0
	v_lshl_add_u64 v[58:59], v[58:59], 2, v[12:13]
	global_load_dword v55, v[58:59], off nt
.LBB0_226:
	s_or_b64 exec, exec, s[38:39]
	v_add_u32_e32 v59, 56, v14
	v_cmp_gt_i32_e32 vcc, s35, v59
	s_and_b64 s[40:41], vcc, s[30:31]
	v_mov_b32_e32 v57, 0
	v_mov_b32_e32 v58, 0
	s_and_saveexec_b64 s[38:39], s[40:41]
	s_cbranch_execz .LBB0_228
	v_mad_i64_i32 v[58:59], s[40:41], s46, v59, 0
	v_lshl_add_u64 v[58:59], v[58:59], 2, v[12:13]
	global_load_dword v58, v[58:59], off nt
.LBB0_228:
	s_or_b64 exec, exec, s[38:39]
	v_add_u32_e32 v59, 58, v14
	v_cmp_gt_i32_e32 vcc, s35, v59
	s_and_b64 s[40:41], vcc, s[30:31]
	s_and_saveexec_b64 s[38:39], s[40:41]
	s_cbranch_execz .LBB0_230
	v_mad_i64_i32 v[60:61], s[40:41], s46, v59, 0
	v_lshl_add_u64 v[60:61], v[60:61], 2, v[12:13]
	global_load_dword v57, v[60:61], off nt
.LBB0_230:
	s_or_b64 exec, exec, s[38:39]
	v_add_u32_e32 v61, 60, v14
	v_cmp_gt_i32_e32 vcc, s35, v61
	s_and_b64 s[40:41], vcc, s[30:31]
	v_mov_b32_e32 v59, 0
	v_mov_b32_e32 v60, 0
	s_and_saveexec_b64 s[38:39], s[40:41]
	s_cbranch_execz .LBB0_232
	v_mad_i64_i32 v[60:61], s[40:41], s46, v61, 0
	v_lshl_add_u64 v[60:61], v[60:61], 2, v[12:13]
	global_load_dword v60, v[60:61], off nt
.LBB0_232:
	s_or_b64 exec, exec, s[38:39]
	v_add_u32_e32 v14, 62, v14
	v_cmp_gt_i32_e32 vcc, s35, v14
	s_and_b64 s[38:39], vcc, s[30:31]
	s_and_saveexec_b64 s[30:31], s[38:39]
	s_cbranch_execz .LBB0_16
	v_mad_i64_i32 v[62:63], s[38:39], s46, v14, 0
	v_lshl_add_u64 v[12:13], v[62:63], 2, v[12:13]
	global_load_dword v59, v[12:13], off nt
	s_branch .LBB0_16

; DI unsigned pk2(float lo, float hi) { f32x2 v = {lo, hi}; bf16x2v b = __builtin_convertvector(v, bf16x2v); return __builtin_bit_cast(unsigned, b); }
; DI void phase_weights(KArgs args, LAS unsigned char* lds, const Ctx& c) {
;     ...
;         for (int t = gw; t < T_ALL; t += NGW) {
;             const float* xr = (t < T_P) ? args->in[0] + (size_t)t * D : args->in[1] + (size_t)(t - T_P) * D;
;             bf16_t* o = WSP(bf16_t, WS_XB) + (size_t)t * D;
; #pragma unroll
;             for (int j = 0; j < 4; ++j) { const f32x4 v = *(const f32x4*)(xr + 4 * lane + 256 * j); u32x2 w; w.x = pk2(v[0], v[1]); w.y = pk2(v[2], v[3]); *(u32x2*)(o + 4 * lane + 256 * j) = w;
;                 *(unsigned*)(WSP(unsigned char, WS_XB8) + (size_t)t * D + 4 * lane + 256 * j) = pk4_fp8(v[0], v[1], v[2], v[3]); }
;         }
.LBB0_241:
	global_load_dwordx4 v[12:15], v2, s[18:19] nt
	v_mov_b32_e32 v5, v3
	s_lshl_b64 s[22:23], s[20:21], 10
	s_lshl_b64 s[20:21], s[20:21], 11
	v_lshl_add_u64 v[16:17], v[6:7], 0, s[20:21]
	v_lshl_add_u64 v[18:19], v[10:11], 0, s[22:23]
	s_mov_b32 s13, 0x7200000
	s_add_u32 s8, s8, s10
	s_addc_u32 s9, s9, s11
	s_add_u32 s14, s14, s16
	s_addc_u32 s15, s15, s17
	s_cmp_gt_i32 s8, 0x13fff
	s_waitcnt vmcnt(0)
	v_cvt_pk_fp8_f32 v5, v12, v13
	v_cvt_pk_bf16_f32 v12, v12, v13
	v_cvt_pk_bf16_f32 v13, v14, v15
	v_cvt_pk_fp8_f32 v5, v14, v15 op_sel:[0,0,1]
	global_store_dwordx2 v[16:17], v[12:13], off
	global_store_dword v[18:19], v5, off
	global_load_dwordx4 v[12:15], v2, s[18:19] offset:1024 nt
	v_mov_b32_e32 v5, v3
	v_lshl_add_u64 v[18:19], v[8:9], 0, s[22:23]
	v_add_co_u32_e32 v18, vcc, s13, v18
	s_waitcnt vmcnt(0)
	v_cvt_pk_fp8_f32 v5, v12, v13
	v_cvt_pk_bf16_f32 v12, v12, v13
	v_cvt_pk_bf16_f32 v13, v14, v15
	v_addc_co_u32_e32 v19, vcc, 0, v19, vcc
	v_cvt_pk_fp8_f32 v5, v14, v15 op_sel:[0,0,1]
	global_store_dwordx2 v[16:17], v[12:13], off offset:512
	global_store_dword v[18:19], v5, off offset:256
	global_load_dwordx4 v[12:15], v2, s[18:19] offset:2048 nt
	v_mov_b32_e32 v5, v3
	s_waitcnt vmcnt(0)
	v_cvt_pk_fp8_f32 v5, v12, v13
	v_cvt_pk_bf16_f32 v12, v12, v13
	v_cvt_pk_bf16_f32 v13, v14, v15
	v_cvt_pk_fp8_f32 v5, v14, v15 op_sel:[0,0,1]
	global_store_dwordx2 v[16:17], v[12:13], off offset:1024
	global_store_dword v[18:19], v5, off offset:512
	global_load_dwordx4 v[12:15], v2, s[18:19] offset:3072 nt
	v_mov_b32_e32 v5, v3
	s_waitcnt vmcnt(0)
	v_cvt_pk_fp8_f32 v5, v12, v13
	v_cvt_pk_bf16_f32 v12, v12, v13
	v_cvt_pk_bf16_f32 v13, v14, v15
	global_store_dwordx2 v[16:17], v[12:13], off offset:1536
	v_cvt_pk_fp8_f32 v5, v14, v15 op_sel:[0,0,1]
	global_store_dword v[18:19], v5, off offset:768
	s_cbranch_scc1 .LBB0_246

; DI void phase_weights(KArgs args, LAS unsigned char* lds, const Ctx& c) {
;     ...
;         float* cs = WSP(float, WS_CS);
;         for (int i = c.bid * 512 + c.tid; i < 16384 * 32; i += c.G * 512) { const int pos = i >> 5, k = i & 31;
;             const float inv = INV_FREQ[k];
;             const float ang = (float)pos * inv;
;             cs[pos * 64 + k] = cosf(ang); cs[pos * 64 + 32 + k] = sinf(ang); }
.LBB0_246:
	v_lshl_add_u32 v1, s48, 9, v1
	s_mov_b32 s6, 0x80000
	v_cmp_gt_i32_e32 vcc, s6, v1
	s_and_saveexec_b64 s[14:15], vcc
	s_cbranch_execz .LBB0_257
	s_waitcnt lgkmcnt(0)
	s_add_u32 s16, s4, 0x17e00000
	s_addc_u32 s17, s5, 0
	v_lshlrev_b32_e32 v2, 2, v4
	s_getpc_b64 s[4:5]
	s_add_u32 s4, s4, _ZL8INV_FREQ@rel32@lo+4
	s_addc_u32 s5, s5, _ZL8INV_FREQ@rel32@hi+12
	global_load_dword v5, v2, s[4:5] nt
	s_lshl_b32 s13, s33, 9
	s_mov_b64 s[18:19], 0
	s_waitcnt vmcnt(0)
	s_branch .LBB0_249
